# MFMA/LDS interleave in all five GEMM K-loops: the eight A-fragment ds_reads of each second super-phase are issued inside the preceding MFMA block right after the last MFMA reading each register; stati
# baseline (speedup 1.0000x reference)
; #define PG8_STAGE(bufoff, gbase, voff) do { _Pragma("unroll") for (int _i = 0; _i < 2; ++_i) \
;         __builtin_amdgcn_global_load_lds((const unsigned*)((const char*)(gbase) + (voff)[_i]), (PG8_LAS unsigned*)(lds + (bufoff) + ldsw + _i * 8192), 16, 0, 0); } while (0)
; #define PG8_LDA(dst, b, h) do { _Pragma("unroll") for (int m = 0; m < 4; ++m) _Pragma("unroll") for (int k = 0; k < 2; ++k) dst[m][k] = *(const PG8_LAS bf16x8*)(lds + PG8_SA(b, h) + aoff + m * 2048 + k * 1024); } while (0)
; #define PG8_LDB(dst, b, h) do { _Pragma("unroll") for (int n = 0; n < 2; ++n) _Pragma("unroll") for (int k = 0; k < 2; ++k) dst[n][k] = *(const PG8_LAS bf16x8*)(lds + PG8_SB(b, h) + boff + n * 2048 + k * 1024); } while (0)
; #define PG8_MMA(ai, bj, At, Bt) do { __builtin_amdgcn_s_setprio(1); _Pragma("unroll") for (int m = 0; m < 4; ++m) _Pragma("unroll") for (int n = 0; n < 2; ++n) _Pragma("unroll") for (int k = 0; k < 2; ++k) \
;         acc[ai][bj][m][n] = __builtin_amdgcn_mfma_f32_16x16x32_bf16(Bt[n][k], At[m][k], acc[ai][bj][m][n], 0, 0, 0); __builtin_amdgcn_s_setprio(0); } while (0)
; #define PG8_WAIT_V(n) asm volatile("s_waitcnt vmcnt(" #n ")" ::: "memory")
; #define PG8_BAR __builtin_amdgcn_s_barrier()
; template <class Epi, class Sched, bool ALIGN_EPI = false, bool SP2 = false>
; __device__ __forceinline__ void gemm_phase(PG8_LAS unsigned char* lds, const Gemm g, const Sched& S, const Epi& E) {
;     ...
;         for (int t = 0; t < nt; t += 2) {
;             const bool last = (t == nt - 2);
;             const char* a1 = cA + (size_t)(t + 1) * kstep;
;             const char* a2 = last ? nA : cA + (size_t)(t + 2) * kstep; const char* b2 = last ? nB : cB + (size_t)(t + 2) * kstep;
;             const char* a3 = a2 + kstep; const char* b3 = b2 + kstep;
;             if (last && has_next) S.a_ready(nxt);
;             if constexpr (SP2) {
;             PG8_LDB(B0, 0, 0); PG8_LDB(B1, 0, 1); PG8_SCHED; PG8_LDA(At, 0, 0); PG8_STAGE(PG8_SA(1, 1), a1 + hstep, voffA);
;             PG8_WAIT_V(8); PG8_WAIT_L(0); PG8_BAR; PG8_MMA(0, 0, At, B0); PG8_MMA(0, 1, At, B1); PG8_BAR; PG8_SCHED;
;             PG8_LDA(At, 0, 1); PG8_STAGE(PG8_SB(0, 0), b2, voffB); PG8_STAGE(PG8_SB(0, 1), b2 + hstep, voffB); PG8_STAGE(PG8_SA(0, 0), a2, voffA);
;             PG8_WAIT_V(8); PG8_WAIT_L(0); PG8_BAR; PG8_MMA(1, 0, At, B0); PG8_MMA(1, 1, At, B1); PG8_BAR; PG8_SCHED;
.Lprio2_done:
.LBB0_274:
	s_lshr_b32 s32, s21, 1
	s_cmp_eq_u32 s32, 2
	s_cbranch_scc1 .Lp2_vloop
	ds_read_b128 v[146:149], v169
	ds_read_b128 v[150:153], v169 offset:1024
	ds_read_b128 v[178:181], v169 offset:2048
	ds_read_b128 v[182:185], v169 offset:3072
	ds_read_b128 v[186:189], v170
	ds_read_b128 v[190:193], v170 offset:1024
	ds_read_b128 v[194:197], v170 offset:2048
	ds_read_b128 v[198:201], v170 offset:3072
	s_add_u32 s0, s14, 0xfffc0080
	s_addc_u32 s1, s15, -1
	s_cmp_eq_u32 s93, 12
	s_cselect_b32 s53, s45, s1
	s_cselect_b32 s52, s89, s0
	s_cselect_b32 s51, s43, s92
	s_cselect_b32 s50, s90, s91
	v_lshl_add_u64 v[206:207], s[14:15], 0, v[138:139]
	s_add_i32 m0, s56, 0xc000
	ds_read_b128 v[202:205], v171
	ds_read_b128 v[210:213], v171 offset:1024
	ds_read_b128 v[214:217], v171 offset:2048
	ds_read_b128 v[218:221], v171 offset:3072
	ds_read_b128 v[222:225], v171 offset:4096
	ds_read_b128 v[226:229], v171 offset:5120
	ds_read_b128 v[230:233], v171 offset:6144
	ds_read_b128 v[234:237], v171 offset:7168
	global_load_lds_dwordx4 v[206:207], off
	v_lshl_add_u64 v[206:207], s[14:15], 0, v[140:141]
	s_add_i32 m0, s56, 0xe000
	s_nop 0
	global_load_lds_dwordx4 v[206:207], off
	s_waitcnt vmcnt(8)
	s_waitcnt lgkmcnt(0)
	s_barrier
	s_waitcnt lgkmcnt(0)
	v_mfma_f32_16x16x32_bf16 v[124:127], v[146:149], v[202:205], v[124:127]
	v_mfma_f32_16x16x32_bf16 v[120:123], v[178:181], v[202:205], v[120:123]
	v_mfma_f32_16x16x32_bf16 v[112:115], v[146:149], v[214:217], v[112:115]
	v_mfma_f32_16x16x32_bf16 v[104:107], v[178:181], v[214:217], v[104:107]
	v_mfma_f32_16x16x32_bf16 v[96:99], v[146:149], v[222:225], v[96:99]
	v_mfma_f32_16x16x32_bf16 v[88:91], v[178:181], v[222:225], v[88:91]
	v_mfma_f32_16x16x32_bf16 v[80:83], v[146:149], v[230:233], v[80:83]
	v_mfma_f32_16x16x32_bf16 v[72:75], v[178:181], v[230:233], v[72:75]
	v_mfma_f32_16x16x32_bf16 v[124:127], v[150:153], v[210:213], v[124:127]
	v_mfma_f32_16x16x32_bf16 v[120:123], v[182:185], v[210:213], v[120:123]
	v_mfma_f32_16x16x32_bf16 v[112:115], v[150:153], v[218:221], v[112:115]
	v_mfma_f32_16x16x32_bf16 v[104:107], v[182:185], v[218:221], v[104:107]
	v_mfma_f32_16x16x32_bf16 v[96:99], v[150:153], v[226:229], v[96:99]
	v_mfma_f32_16x16x32_bf16 v[88:91], v[182:185], v[226:229], v[88:91]
	v_mfma_f32_16x16x32_bf16 v[80:83], v[150:153], v[234:237], v[80:83]
	v_mfma_f32_16x16x32_bf16 v[72:75], v[182:185], v[234:237], v[72:75]
	v_mfma_f32_16x16x32_bf16 v[116:119], v[186:189], v[202:205], v[116:119]
	v_mfma_f32_16x16x32_bf16 v[108:111], v[194:197], v[202:205], v[108:111]
	ds_read_b128 v[202:205], v171 offset:16384
	v_mfma_f32_16x16x32_bf16 v[100:103], v[186:189], v[214:217], v[100:103]
	v_mfma_f32_16x16x32_bf16 v[92:95], v[194:197], v[214:217], v[92:95]
	ds_read_b128 v[214:217], v171 offset:18432
	v_mfma_f32_16x16x32_bf16 v[84:87], v[186:189], v[222:225], v[84:87]
	v_mfma_f32_16x16x32_bf16 v[76:79], v[194:197], v[222:225], v[76:79]
	ds_read_b128 v[222:225], v171 offset:20480
	v_mfma_f32_16x16x32_bf16 v[68:71], v[186:189], v[230:233], v[68:71]
	v_mfma_f32_16x16x32_bf16 v[64:67], v[194:197], v[230:233], v[64:67]
	ds_read_b128 v[230:233], v171 offset:22528
	v_mfma_f32_16x16x32_bf16 v[116:119], v[190:193], v[210:213], v[116:119]
	v_mfma_f32_16x16x32_bf16 v[108:111], v[198:201], v[210:213], v[108:111]
	ds_read_b128 v[210:213], v171 offset:17408
	v_mfma_f32_16x16x32_bf16 v[100:103], v[190:193], v[218:221], v[100:103]
	v_mfma_f32_16x16x32_bf16 v[92:95], v[198:201], v[218:221], v[92:95]
	ds_read_b128 v[218:221], v171 offset:19456
	v_mfma_f32_16x16x32_bf16 v[84:87], v[190:193], v[226:229], v[84:87]
	v_mfma_f32_16x16x32_bf16 v[76:79], v[198:201], v[226:229], v[76:79]
	ds_read_b128 v[226:229], v171 offset:21504
	v_mfma_f32_16x16x32_bf16 v[68:71], v[190:193], v[234:237], v[68:71]
	v_mfma_f32_16x16x32_bf16 v[64:67], v[198:201], v[234:237], v[64:67]
	ds_read_b128 v[234:237], v171 offset:23552
	s_barrier
	s_add_i32 s0, s74, s29
	v_lshl_add_u64 v[206:207], s[50:51], 0, v[132:133]
	s_mov_b32 m0, s0
	global_load_lds_dwordx4 v[206:207], off
	s_add_i32 m0, s0, 0x2000
	s_add_u32 s94, s50, 0x40000
	v_lshl_add_u64 v[238:239], s[50:51], 0, v[128:129]
	s_addc_u32 s95, s51, 0
	s_add_i32 s0, s75, s29
	global_load_lds_dwordx4 v[238:239], off
	v_lshl_add_u64 v[240:241], s[94:95], 0, v[132:133]
	s_mov_b32 m0, s0
	v_lshl_add_u64 v[242:243], s[52:53], 0, v[130:131]
	global_load_lds_dwordx4 v[240:241], off
	v_lshl_add_u64 v[240:241], s[94:95], 0, v[128:129]
	s_add_i32 m0, s0, 0x2000
	s_nop 0
	global_load_lds_dwordx4 v[240:241], off
	v_lshl_add_u64 v[240:241], s[52:53], 0, v[134:135]
	s_mov_b32 m0, s56
	s_nop 0
	global_load_lds_dwordx4 v[240:241], off
	s_mov_b32 m0, s57
	s_nop 0
	global_load_lds_dwordx4 v[242:243], off
	s_waitcnt vmcnt(8)
	s_waitcnt lgkmcnt(0)
	s_barrier
; #define PG8_STAGE(bufoff, gbase, voff) do { _Pragma("unroll") for (int _i = 0; _i < 2; ++_i) \
;         __builtin_amdgcn_global_load_lds((const unsigned*)((const char*)(gbase) + (voff)[_i]), (PG8_LAS unsigned*)(lds + (bufoff) + ldsw + _i * 8192), 16, 0, 0); } while (0)
; #define PG8_LDA(dst, b, h) do { _Pragma("unroll") for (int m = 0; m < 4; ++m) _Pragma("unroll") for (int k = 0; k < 2; ++k) dst[m][k] = *(const PG8_LAS bf16x8*)(lds + PG8_SA(b, h) + aoff + m * 2048 + k * 1024); } while (0)
; #define PG8_LDB(dst, b, h) do { _Pragma("unroll") for (int n = 0; n < 2; ++n) _Pragma("unroll") for (int k = 0; k < 2; ++k) dst[n][k] = *(const PG8_LAS bf16x8*)(lds + PG8_SB(b, h) + boff + n * 2048 + k * 1024); } while (0)
; #define PG8_MMA(ai, bj, At, Bt) do { __builtin_amdgcn_s_setprio(1); _Pragma("unroll") for (int m = 0; m < 4; ++m) _Pragma("unroll") for (int n = 0; n < 2; ++n) _Pragma("unroll") for (int k = 0; k < 2; ++k) \
;         acc[ai][bj][m][n] = __builtin_amdgcn_mfma_f32_16x16x32_bf16(Bt[n][k], At[m][k], acc[ai][bj][m][n], 0, 0, 0); __builtin_amdgcn_s_setprio(0); } while (0)
; #define PG8_WAIT_V(n) asm volatile("s_waitcnt vmcnt(" #n ")" ::: "memory")
; #define PG8_WAIT_L(n) asm volatile("s_waitcnt lgkmcnt(" #n ")" ::: "memory")
; #define PG8_BAR __builtin_amdgcn_s_barrier()
; #define PG8_SCHED __builtin_amdgcn_sched_barrier(0)
; template <class Epi, class Sched, bool ALIGN_EPI = false, bool SP2 = false>
; __device__ __forceinline__ void gemm_phase(PG8_LAS unsigned char* lds, const Gemm g, const Sched& S, const Epi& E) {
;     ...
;             PG8_WAIT_V(8); PG8_WAIT_L(0); PG8_BAR; PG8_MMA(1, 0, At, B0); PG8_MMA(1, 1, At, B1); PG8_BAR; PG8_SCHED;
;             PG8_LDB(B0, 1, 0); PG8_LDB(B1, 1, 1); PG8_SCHED; PG8_LDA(At, 1, 0); PG8_STAGE(PG8_SA(0, 1), a2 + hstep, voffA);
;             PG8_WAIT_V(8); PG8_WAIT_L(0); PG8_BAR; PG8_MMA(0, 0, At, B0); PG8_MMA(0, 1, At, B1); PG8_BAR; PG8_SCHED;
	s_waitcnt lgkmcnt(0)
	v_mfma_f32_16x16x32_bf16 v[60:63], v[146:149], v[202:205], v[60:63]
	v_mfma_f32_16x16x32_bf16 v[56:59], v[178:181], v[202:205], v[56:59]
	v_mfma_f32_16x16x32_bf16 v[48:51], v[146:149], v[214:217], v[48:51]
	v_mfma_f32_16x16x32_bf16 v[40:43], v[178:181], v[214:217], v[40:43]
	v_mfma_f32_16x16x32_bf16 v[32:35], v[146:149], v[222:225], v[32:35]
	v_mfma_f32_16x16x32_bf16 v[24:27], v[178:181], v[222:225], v[24:27]
	v_mfma_f32_16x16x32_bf16 v[16:19], v[146:149], v[230:233], v[16:19]
	v_mfma_f32_16x16x32_bf16 v[8:11], v[178:181], v[230:233], v[8:11]
	v_mfma_f32_16x16x32_bf16 v[60:63], v[150:153], v[210:213], v[60:63]
	v_mfma_f32_16x16x32_bf16 v[56:59], v[182:185], v[210:213], v[56:59]
	v_mfma_f32_16x16x32_bf16 v[48:51], v[150:153], v[218:221], v[48:51]
	v_mfma_f32_16x16x32_bf16 v[40:43], v[182:185], v[218:221], v[40:43]
	v_mfma_f32_16x16x32_bf16 v[32:35], v[150:153], v[226:229], v[32:35]
	v_mfma_f32_16x16x32_bf16 v[24:27], v[182:185], v[226:229], v[24:27]
	v_mfma_f32_16x16x32_bf16 v[16:19], v[150:153], v[234:237], v[16:19]
	v_mfma_f32_16x16x32_bf16 v[8:11], v[182:185], v[234:237], v[8:11]
	v_mfma_f32_16x16x32_bf16 v[52:55], v[186:189], v[202:205], v[52:55]
	v_mfma_f32_16x16x32_bf16 v[44:47], v[194:197], v[202:205], v[44:47]
	v_mfma_f32_16x16x32_bf16 v[36:39], v[186:189], v[214:217], v[36:39]
	v_mfma_f32_16x16x32_bf16 v[28:31], v[194:197], v[214:217], v[28:31]
	v_mfma_f32_16x16x32_bf16 v[20:23], v[186:189], v[222:225], v[20:23]
	v_mfma_f32_16x16x32_bf16 v[12:15], v[194:197], v[222:225], v[12:15]
	v_mfma_f32_16x16x32_bf16 v[4:7], v[186:189], v[230:233], v[4:7]
	v_mfma_f32_16x16x32_bf16 v[0:3], v[194:197], v[230:233], v[0:3]
	v_mfma_f32_16x16x32_bf16 v[52:55], v[190:193], v[210:213], v[52:55]
	v_mfma_f32_16x16x32_bf16 v[44:47], v[198:201], v[210:213], v[44:47]
	v_mfma_f32_16x16x32_bf16 v[36:39], v[190:193], v[218:221], v[36:39]
	v_mfma_f32_16x16x32_bf16 v[28:31], v[198:201], v[218:221], v[28:31]
	v_mfma_f32_16x16x32_bf16 v[20:23], v[190:193], v[226:229], v[20:23]
	v_mfma_f32_16x16x32_bf16 v[12:15], v[198:201], v[226:229], v[12:15]
	v_mfma_f32_16x16x32_bf16 v[4:7], v[190:193], v[234:237], v[4:7]
	v_mfma_f32_16x16x32_bf16 v[0:3], v[198:201], v[234:237], v[0:3]
	s_barrier
	s_add_i32 s0, 0, 0x18000
	v_add_u32_e32 v136, s0, v158
	s_add_i32 s1, 0, 0x1c000
	ds_read_b128 v[146:149], v136
	ds_read_b128 v[150:153], v136 offset:1024
	ds_read_b128 v[178:181], v136 offset:2048
	ds_read_b128 v[182:185], v136 offset:3072
	v_add_u32_e32 v136, s1, v158
	ds_read_b128 v[186:189], v136
	ds_read_b128 v[190:193], v136 offset:1024
	ds_read_b128 v[194:197], v136 offset:2048
	ds_read_b128 v[198:201], v136 offset:3072
	s_add_u32 s52, s52, 0x40000
	s_addc_u32 s53, s53, 0
	s_mov_b32 m0, s59
	v_lshl_add_u64 v[244:245], s[52:53], 0, v[134:135]
	ds_read_b128 v[202:205], v171 offset:32768
	ds_read_b128 v[210:213], v171 offset:33792
	ds_read_b128 v[214:217], v171 offset:34816
	ds_read_b128 v[218:221], v171 offset:35840
	ds_read_b128 v[222:225], v171 offset:36864
	ds_read_b128 v[226:229], v171 offset:37888
	ds_read_b128 v[230:233], v171 offset:38912
	ds_read_b128 v[234:237], v171 offset:39936
	global_load_lds_dwordx4 v[244:245], off
	v_lshl_add_u64 v[244:245], s[52:53], 0, v[130:131]
	s_mov_b32 m0, s60
	s_nop 0
	global_load_lds_dwordx4 v[244:245], off
	s_waitcnt vmcnt(8)
	s_waitcnt lgkmcnt(0)
	s_barrier
; #define PG8_STAGE(bufoff, gbase, voff) do { _Pragma("unroll") for (int _i = 0; _i < 2; ++_i) \
;         __builtin_amdgcn_global_load_lds((const unsigned*)((const char*)(gbase) + (voff)[_i]), (PG8_LAS unsigned*)(lds + (bufoff) + ldsw + _i * 8192), 16, 0, 0); } while (0)
; #define PG8_LDA(dst, b, h) do { _Pragma("unroll") for (int m = 0; m < 4; ++m) _Pragma("unroll") for (int k = 0; k < 2; ++k) dst[m][k] = *(const PG8_LAS bf16x8*)(lds + PG8_SA(b, h) + aoff + m * 2048 + k * 1024); } while (0)
; #define PG8_MMA(ai, bj, At, Bt) do { __builtin_amdgcn_s_setprio(1); _Pragma("unroll") for (int m = 0; m < 4; ++m) _Pragma("unroll") for (int n = 0; n < 2; ++n) _Pragma("unroll") for (int k = 0; k < 2; ++k) \
;         acc[ai][bj][m][n] = __builtin_amdgcn_mfma_f32_16x16x32_bf16(Bt[n][k], At[m][k], acc[ai][bj][m][n], 0, 0, 0); __builtin_amdgcn_s_setprio(0); } while (0)
; #define PG8_WAIT_V(n) asm volatile("s_waitcnt vmcnt(" #n ")" ::: "memory")
; #define PG8_WAIT_L(n) asm volatile("s_waitcnt lgkmcnt(" #n ")" ::: "memory")
; #define PG8_BAR __builtin_amdgcn_s_barrier()
; #define PG8_SCHED __builtin_amdgcn_sched_barrier(0)
; template <class Epi, class Sched, bool ALIGN_EPI = false, bool SP2 = false>
; __device__ __forceinline__ void gemm_phase(PG8_LAS unsigned char* lds, const Gemm g, const Sched& S, const Epi& E) {
;     ...
;             PG8_WAIT_V(8); PG8_WAIT_L(0); PG8_BAR; PG8_MMA(0, 0, At, B0); PG8_MMA(0, 1, At, B1); PG8_BAR; PG8_SCHED;
;             PG8_LDA(At, 1, 1); PG8_STAGE(PG8_SB(1, 0), b3, voffB); PG8_STAGE(PG8_SB(1, 1), b3 + hstep, voffB); PG8_STAGE(PG8_SA(1, 0), a3, voffA);
;             PG8_WAIT_V(8); PG8_WAIT_L(0); PG8_BAR; PG8_MMA(1, 0, At, B0); PG8_MMA(1, 1, At, B1); PG8_BAR; PG8_SCHED;
	s_waitcnt lgkmcnt(0)
	v_mfma_f32_16x16x32_bf16 v[124:127], v[146:149], v[202:205], v[124:127]
	v_mfma_f32_16x16x32_bf16 v[120:123], v[178:181], v[202:205], v[120:123]
	v_mfma_f32_16x16x32_bf16 v[112:115], v[146:149], v[214:217], v[112:115]
	v_mfma_f32_16x16x32_bf16 v[104:107], v[178:181], v[214:217], v[104:107]
	v_mfma_f32_16x16x32_bf16 v[96:99], v[146:149], v[222:225], v[96:99]
	v_mfma_f32_16x16x32_bf16 v[88:91], v[178:181], v[222:225], v[88:91]
	v_mfma_f32_16x16x32_bf16 v[80:83], v[146:149], v[230:233], v[80:83]
	v_mfma_f32_16x16x32_bf16 v[72:75], v[178:181], v[230:233], v[72:75]
	v_mfma_f32_16x16x32_bf16 v[124:127], v[150:153], v[210:213], v[124:127]
	v_mfma_f32_16x16x32_bf16 v[120:123], v[182:185], v[210:213], v[120:123]
	v_mfma_f32_16x16x32_bf16 v[112:115], v[150:153], v[218:221], v[112:115]
	v_mfma_f32_16x16x32_bf16 v[104:107], v[182:185], v[218:221], v[104:107]
	v_mfma_f32_16x16x32_bf16 v[96:99], v[150:153], v[226:229], v[96:99]
	v_mfma_f32_16x16x32_bf16 v[88:91], v[182:185], v[226:229], v[88:91]
	v_mfma_f32_16x16x32_bf16 v[80:83], v[150:153], v[234:237], v[80:83]
	v_mfma_f32_16x16x32_bf16 v[72:75], v[182:185], v[234:237], v[72:75]
	v_mfma_f32_16x16x32_bf16 v[116:119], v[186:189], v[202:205], v[116:119]
	v_mfma_f32_16x16x32_bf16 v[108:111], v[194:197], v[202:205], v[108:111]
	ds_read_b128 v[202:205], v171 offset:49152
	v_mfma_f32_16x16x32_bf16 v[100:103], v[186:189], v[214:217], v[100:103]
	v_mfma_f32_16x16x32_bf16 v[92:95], v[194:197], v[214:217], v[92:95]
	ds_read_b128 v[214:217], v171 offset:51200
	v_mfma_f32_16x16x32_bf16 v[84:87], v[186:189], v[222:225], v[84:87]
	v_mfma_f32_16x16x32_bf16 v[76:79], v[194:197], v[222:225], v[76:79]
	ds_read_b128 v[222:225], v171 offset:53248
	v_mfma_f32_16x16x32_bf16 v[68:71], v[186:189], v[230:233], v[68:71]
	v_mfma_f32_16x16x32_bf16 v[64:67], v[194:197], v[230:233], v[64:67]
	ds_read_b128 v[230:233], v171 offset:55296
	v_mfma_f32_16x16x32_bf16 v[116:119], v[190:193], v[210:213], v[116:119]
	v_mfma_f32_16x16x32_bf16 v[108:111], v[198:201], v[210:213], v[108:111]
	ds_read_b128 v[210:213], v171 offset:50176
	v_mfma_f32_16x16x32_bf16 v[100:103], v[190:193], v[218:221], v[100:103]
	v_mfma_f32_16x16x32_bf16 v[92:95], v[198:201], v[218:221], v[92:95]
	ds_read_b128 v[218:221], v171 offset:52224
	v_mfma_f32_16x16x32_bf16 v[84:87], v[190:193], v[226:229], v[84:87]
	v_mfma_f32_16x16x32_bf16 v[76:79], v[198:201], v[226:229], v[76:79]
	ds_read_b128 v[226:229], v171 offset:54272
	v_mfma_f32_16x16x32_bf16 v[68:71], v[190:193], v[234:237], v[68:71]
	v_mfma_f32_16x16x32_bf16 v[64:67], v[198:201], v[234:237], v[64:67]
	ds_read_b128 v[234:237], v171 offset:56320
	s_barrier
	s_add_i32 s0, s0, s29
	v_lshl_add_u64 v[206:207], v[206:207], 0, s[38:39]
	s_mov_b32 m0, s0
	global_load_lds_dwordx4 v[206:207], off
	s_add_i32 m0, s0, 0x2000
	s_add_u32 s50, s50, 0x40080
	v_lshl_add_u64 v[206:207], v[238:239], 0, s[38:39]
	s_addc_u32 s51, s51, 0
	s_add_i32 s0, s1, s29
	global_load_lds_dwordx4 v[206:207], off
	v_lshl_add_u64 v[206:207], s[50:51], 0, v[132:133]
	s_mov_b32 m0, s0
	s_nop 0
	global_load_lds_dwordx4 v[206:207], off
	v_lshl_add_u64 v[206:207], s[50:51], 0, v[128:129]
	s_add_i32 m0, s0, 0x2000
	s_nop 0
	global_load_lds_dwordx4 v[206:207], off
	v_lshl_add_u64 v[206:207], v[240:241], 0, s[38:39]
	s_mov_b32 m0, s69
	s_nop 0
	global_load_lds_dwordx4 v[206:207], off
	v_lshl_add_u64 v[206:207], v[242:243], 0, s[38:39]
	s_mov_b32 m0, s70
	s_nop 0
	global_load_lds_dwordx4 v[206:207], off
	s_waitcnt vmcnt(8)
	s_waitcnt lgkmcnt(0)
	s_barrier
	s_waitcnt lgkmcnt(0)
	v_mfma_f32_16x16x32_bf16 v[60:63], v[146:149], v[202:205], v[60:63]
	v_mfma_f32_16x16x32_bf16 v[56:59], v[178:181], v[202:205], v[56:59]
	v_mfma_f32_16x16x32_bf16 v[48:51], v[146:149], v[214:217], v[48:51]
	v_mfma_f32_16x16x32_bf16 v[40:43], v[178:181], v[214:217], v[40:43]
	v_mfma_f32_16x16x32_bf16 v[32:35], v[146:149], v[222:225], v[32:35]
	v_mfma_f32_16x16x32_bf16 v[24:27], v[178:181], v[222:225], v[24:27]
	v_mfma_f32_16x16x32_bf16 v[16:19], v[146:149], v[230:233], v[16:19]
	v_mfma_f32_16x16x32_bf16 v[8:11], v[178:181], v[230:233], v[8:11]
	v_mfma_f32_16x16x32_bf16 v[60:63], v[150:153], v[210:213], v[60:63]
	v_mfma_f32_16x16x32_bf16 v[56:59], v[182:185], v[210:213], v[56:59]
	v_mfma_f32_16x16x32_bf16 v[48:51], v[150:153], v[218:221], v[48:51]
	v_mfma_f32_16x16x32_bf16 v[40:43], v[182:185], v[218:221], v[40:43]
	v_mfma_f32_16x16x32_bf16 v[32:35], v[150:153], v[226:229], v[32:35]
	v_mfma_f32_16x16x32_bf16 v[24:27], v[182:185], v[226:229], v[24:27]
	v_mfma_f32_16x16x32_bf16 v[16:19], v[150:153], v[234:237], v[16:19]
	v_mfma_f32_16x16x32_bf16 v[8:11], v[182:185], v[234:237], v[8:11]
	v_mfma_f32_16x16x32_bf16 v[52:55], v[186:189], v[202:205], v[52:55]
	v_mfma_f32_16x16x32_bf16 v[44:47], v[194:197], v[202:205], v[44:47]
	v_mfma_f32_16x16x32_bf16 v[36:39], v[186:189], v[214:217], v[36:39]
	v_mfma_f32_16x16x32_bf16 v[28:31], v[194:197], v[214:217], v[28:31]
	v_mfma_f32_16x16x32_bf16 v[20:23], v[186:189], v[222:225], v[20:23]
	v_mfma_f32_16x16x32_bf16 v[12:15], v[194:197], v[222:225], v[12:15]
	v_mfma_f32_16x16x32_bf16 v[4:7], v[186:189], v[230:233], v[4:7]
	v_mfma_f32_16x16x32_bf16 v[0:3], v[194:197], v[230:233], v[0:3]
	v_mfma_f32_16x16x32_bf16 v[52:55], v[190:193], v[210:213], v[52:55]
	v_mfma_f32_16x16x32_bf16 v[44:47], v[198:201], v[210:213], v[44:47]
	v_mfma_f32_16x16x32_bf16 v[36:39], v[190:193], v[218:221], v[36:39]
	v_mfma_f32_16x16x32_bf16 v[28:31], v[198:201], v[218:221], v[28:31]
	v_mfma_f32_16x16x32_bf16 v[20:23], v[190:193], v[226:229], v[20:23]
	v_mfma_f32_16x16x32_bf16 v[12:15], v[198:201], v[226:229], v[12:15]
	v_mfma_f32_16x16x32_bf16 v[4:7], v[190:193], v[234:237], v[4:7]
	v_mfma_f32_16x16x32_bf16 v[0:3], v[198:201], v[234:237], v[0:3]
	s_barrier
	s_add_i32 s93, s93, 2
	s_add_u32 s14, s14, 0x100
	s_addc_u32 s15, s15, 0
	s_add_u32 s91, s91, 0x100
	s_addc_u32 s92, s92, 0
	s_cmp_gt_u32 s93, 13
	s_cbranch_scc0 .LBB0_274

; #define PG8_STAGE(bufoff, gbase, voff) do { _Pragma("unroll") for (int _i = 0; _i < 2; ++_i) \
;         __builtin_amdgcn_global_load_lds((const unsigned*)((const char*)(gbase) + (voff)[_i]), (PG8_LAS unsigned*)(lds + (bufoff) + ldsw + _i * 8192), 16, 0, 0); } while (0)
; #define PG8_LDA(dst, b, h) do { _Pragma("unroll") for (int m = 0; m < 4; ++m) _Pragma("unroll") for (int k = 0; k < 2; ++k) dst[m][k] = *(const PG8_LAS bf16x8*)(lds + PG8_SA(b, h) + aoff + m * 2048 + k * 1024); } while (0)
; #define PG8_LDB(dst, b, h) do { _Pragma("unroll") for (int n = 0; n < 2; ++n) _Pragma("unroll") for (int k = 0; k < 2; ++k) dst[n][k] = *(const PG8_LAS bf16x8*)(lds + PG8_SB(b, h) + boff + n * 2048 + k * 1024); } while (0)
; #define PG8_MMA(ai, bj, At, Bt) do { __builtin_amdgcn_s_setprio(1); _Pragma("unroll") for (int m = 0; m < 4; ++m) _Pragma("unroll") for (int n = 0; n < 2; ++n) _Pragma("unroll") for (int k = 0; k < 2; ++k) \
;         acc[ai][bj][m][n] = __builtin_amdgcn_mfma_f32_16x16x32_bf16(Bt[n][k], At[m][k], acc[ai][bj][m][n], 0, 0, 0); __builtin_amdgcn_s_setprio(0); } while (0)
; #define PG8_WAIT_V(n) asm volatile("s_waitcnt vmcnt(" #n ")" ::: "memory")
; #define PG8_BAR __builtin_amdgcn_s_barrier()
; template <class Epi, class Sched, bool ALIGN_EPI = false, bool SP2 = false>
; __device__ __forceinline__ void gemm_phase(PG8_LAS unsigned char* lds, const Gemm g, const Sched& S, const Epi& E) {
;     ...
;         for (int t = 0; t < nt; t += 2) {
;             const bool last = (t == nt - 2);
;             const char* a1 = cA + (size_t)(t + 1) * kstep;
;             const char* a2 = last ? nA : cA + (size_t)(t + 2) * kstep; const char* b2 = last ? nB : cB + (size_t)(t + 2) * kstep;
;             const char* a3 = a2 + kstep; const char* b3 = b2 + kstep;
;             if (last && has_next) S.a_ready(nxt);
;             if constexpr (SP2) {
;             PG8_LDB(B0, 0, 0); PG8_LDB(B1, 0, 1); PG8_SCHED; PG8_LDA(At, 0, 0); PG8_STAGE(PG8_SA(1, 1), a1 + hstep, voffA);
;             PG8_WAIT_V(8); PG8_WAIT_L(0); PG8_BAR; PG8_MMA(0, 0, At, B0); PG8_MMA(0, 1, At, B1); PG8_BAR; PG8_SCHED;
;             PG8_LDA(At, 0, 1); PG8_STAGE(PG8_SB(0, 0), b2, voffB); PG8_STAGE(PG8_SB(0, 1), b2 + hstep, voffB); PG8_STAGE(PG8_SA(0, 0), a2, voffA);
;             PG8_WAIT_V(8); PG8_WAIT_L(0); PG8_BAR; PG8_MMA(1, 0, At, B0); PG8_MMA(1, 1, At, B1); PG8_BAR; PG8_SCHED;
.Lp2_vloop:
	ds_read_b128 v[146:149], v169
	ds_read_b128 v[150:153], v169 offset:1024
	ds_read_b128 v[178:181], v169 offset:2048
	ds_read_b128 v[182:185], v169 offset:3072
	ds_read_b128 v[186:189], v170
	ds_read_b128 v[190:193], v170 offset:1024
	ds_read_b128 v[194:197], v170 offset:2048
	ds_read_b128 v[198:201], v170 offset:3072
	s_add_u32 s0, s14, 0xfffc0080
	s_addc_u32 s1, s15, -1
	s_cmp_eq_u32 s93, 12
	s_cselect_b32 s53, s45, s1
	s_cselect_b32 s52, s89, s0
	s_cselect_b32 s51, s43, s92
	s_cselect_b32 s50, s90, s91
	v_lshl_add_u64 v[206:207], s[14:15], 0, v[138:139]
	s_add_i32 m0, s56, 0xc000
	ds_read_b128 v[202:205], v171
	ds_read_b128 v[210:213], v171 offset:1024
	ds_read_b128 v[214:217], v171 offset:2048
	ds_read_b128 v[218:221], v171 offset:3072
	ds_read_b128 v[222:225], v171 offset:4096
	ds_read_b128 v[226:229], v171 offset:5120
	ds_read_b128 v[230:233], v171 offset:6144
	ds_read_b128 v[234:237], v171 offset:7168
	global_load_lds_dwordx4 v[206:207], off
	v_lshl_add_u64 v[206:207], s[14:15], 0, v[140:141]
	s_add_i32 m0, s56, 0xe000
	s_nop 0
	global_load_lds_dwordx4 v[206:207], off
	s_waitcnt vmcnt(8)
	s_waitcnt lgkmcnt(0)
	s_barrier
	s_waitcnt lgkmcnt(0)
	v_mfma_f32_16x16x32_bf16 v[124:127], v[202:205], v[146:149], v[124:127]
	v_mfma_f32_16x16x32_bf16 v[120:123], v[202:205], v[178:181], v[120:123]
	v_mfma_f32_16x16x32_bf16 v[112:115], v[214:217], v[146:149], v[112:115]
	v_mfma_f32_16x16x32_bf16 v[104:107], v[214:217], v[178:181], v[104:107]
	v_mfma_f32_16x16x32_bf16 v[96:99], v[222:225], v[146:149], v[96:99]
	v_mfma_f32_16x16x32_bf16 v[88:91], v[222:225], v[178:181], v[88:91]
	v_mfma_f32_16x16x32_bf16 v[80:83], v[230:233], v[146:149], v[80:83]
	v_mfma_f32_16x16x32_bf16 v[72:75], v[230:233], v[178:181], v[72:75]
	v_mfma_f32_16x16x32_bf16 v[124:127], v[210:213], v[150:153], v[124:127]
	v_mfma_f32_16x16x32_bf16 v[120:123], v[210:213], v[182:185], v[120:123]
	v_mfma_f32_16x16x32_bf16 v[112:115], v[218:221], v[150:153], v[112:115]
	v_mfma_f32_16x16x32_bf16 v[104:107], v[218:221], v[182:185], v[104:107]
	v_mfma_f32_16x16x32_bf16 v[96:99], v[226:229], v[150:153], v[96:99]
	v_mfma_f32_16x16x32_bf16 v[88:91], v[226:229], v[182:185], v[88:91]
	v_mfma_f32_16x16x32_bf16 v[80:83], v[234:237], v[150:153], v[80:83]
	v_mfma_f32_16x16x32_bf16 v[72:75], v[234:237], v[182:185], v[72:75]
	v_mfma_f32_16x16x32_bf16 v[116:119], v[202:205], v[186:189], v[116:119]
	v_mfma_f32_16x16x32_bf16 v[108:111], v[202:205], v[194:197], v[108:111]
	ds_read_b128 v[202:205], v171 offset:16384
	v_mfma_f32_16x16x32_bf16 v[100:103], v[214:217], v[186:189], v[100:103]
	v_mfma_f32_16x16x32_bf16 v[92:95], v[214:217], v[194:197], v[92:95]
	ds_read_b128 v[214:217], v171 offset:18432
	v_mfma_f32_16x16x32_bf16 v[84:87], v[222:225], v[186:189], v[84:87]
	v_mfma_f32_16x16x32_bf16 v[76:79], v[222:225], v[194:197], v[76:79]
	ds_read_b128 v[222:225], v171 offset:20480
	v_mfma_f32_16x16x32_bf16 v[68:71], v[230:233], v[186:189], v[68:71]
	v_mfma_f32_16x16x32_bf16 v[64:67], v[230:233], v[194:197], v[64:67]
	ds_read_b128 v[230:233], v171 offset:22528
	v_mfma_f32_16x16x32_bf16 v[116:119], v[210:213], v[190:193], v[116:119]
	v_mfma_f32_16x16x32_bf16 v[108:111], v[210:213], v[198:201], v[108:111]
	ds_read_b128 v[210:213], v171 offset:17408
	v_mfma_f32_16x16x32_bf16 v[100:103], v[218:221], v[190:193], v[100:103]
	v_mfma_f32_16x16x32_bf16 v[92:95], v[218:221], v[198:201], v[92:95]
	ds_read_b128 v[218:221], v171 offset:19456
	v_mfma_f32_16x16x32_bf16 v[84:87], v[226:229], v[190:193], v[84:87]
	v_mfma_f32_16x16x32_bf16 v[76:79], v[226:229], v[198:201], v[76:79]
	ds_read_b128 v[226:229], v171 offset:21504
	v_mfma_f32_16x16x32_bf16 v[68:71], v[234:237], v[190:193], v[68:71]
	v_mfma_f32_16x16x32_bf16 v[64:67], v[234:237], v[198:201], v[64:67]
	ds_read_b128 v[234:237], v171 offset:23552
	s_barrier
	s_add_i32 s0, s74, s29
	v_lshl_add_u64 v[206:207], s[50:51], 0, v[132:133]
	s_mov_b32 m0, s0
	global_load_lds_dwordx4 v[206:207], off
	s_add_i32 m0, s0, 0x2000
	s_add_u32 s94, s50, 0x40000
	v_lshl_add_u64 v[238:239], s[50:51], 0, v[128:129]
	s_addc_u32 s95, s51, 0
	s_add_i32 s0, s75, s29
	global_load_lds_dwordx4 v[238:239], off
	v_lshl_add_u64 v[240:241], s[94:95], 0, v[132:133]
	s_mov_b32 m0, s0
	v_lshl_add_u64 v[242:243], s[52:53], 0, v[130:131]
	global_load_lds_dwordx4 v[240:241], off
	v_lshl_add_u64 v[240:241], s[94:95], 0, v[128:129]
	s_add_i32 m0, s0, 0x2000
	s_nop 0
	global_load_lds_dwordx4 v[240:241], off
	v_lshl_add_u64 v[240:241], s[52:53], 0, v[134:135]
	s_mov_b32 m0, s56
	s_nop 0
	global_load_lds_dwordx4 v[240:241], off
	s_mov_b32 m0, s57
	s_nop 0
	global_load_lds_dwordx4 v[242:243], off
	s_waitcnt vmcnt(8)
	s_waitcnt lgkmcnt(0)
	s_barrier
; #define PG8_STAGE(bufoff, gbase, voff) do { _Pragma("unroll") for (int _i = 0; _i < 2; ++_i) \
;         __builtin_amdgcn_global_load_lds((const unsigned*)((const char*)(gbase) + (voff)[_i]), (PG8_LAS unsigned*)(lds + (bufoff) + ldsw + _i * 8192), 16, 0, 0); } while (0)
; #define PG8_LDA(dst, b, h) do { _Pragma("unroll") for (int m = 0; m < 4; ++m) _Pragma("unroll") for (int k = 0; k < 2; ++k) dst[m][k] = *(const PG8_LAS bf16x8*)(lds + PG8_SA(b, h) + aoff + m * 2048 + k * 1024); } while (0)
; #define PG8_LDB(dst, b, h) do { _Pragma("unroll") for (int n = 0; n < 2; ++n) _Pragma("unroll") for (int k = 0; k < 2; ++k) dst[n][k] = *(const PG8_LAS bf16x8*)(lds + PG8_SB(b, h) + boff + n * 2048 + k * 1024); } while (0)
; #define PG8_MMA(ai, bj, At, Bt) do { __builtin_amdgcn_s_setprio(1); _Pragma("unroll") for (int m = 0; m < 4; ++m) _Pragma("unroll") for (int n = 0; n < 2; ++n) _Pragma("unroll") for (int k = 0; k < 2; ++k) \
;         acc[ai][bj][m][n] = __builtin_amdgcn_mfma_f32_16x16x32_bf16(Bt[n][k], At[m][k], acc[ai][bj][m][n], 0, 0, 0); __builtin_amdgcn_s_setprio(0); } while (0)
; #define PG8_WAIT_V(n) asm volatile("s_waitcnt vmcnt(" #n ")" ::: "memory")
; #define PG8_WAIT_L(n) asm volatile("s_waitcnt lgkmcnt(" #n ")" ::: "memory")
; #define PG8_BAR __builtin_amdgcn_s_barrier()
; #define PG8_SCHED __builtin_amdgcn_sched_barrier(0)
; template <class Epi, class Sched, bool ALIGN_EPI = false, bool SP2 = false>
; __device__ __forceinline__ void gemm_phase(PG8_LAS unsigned char* lds, const Gemm g, const Sched& S, const Epi& E) {
;     ...
;             PG8_WAIT_V(8); PG8_WAIT_L(0); PG8_BAR; PG8_MMA(1, 0, At, B0); PG8_MMA(1, 1, At, B1); PG8_BAR; PG8_SCHED;
;             PG8_LDB(B0, 1, 0); PG8_LDB(B1, 1, 1); PG8_SCHED; PG8_LDA(At, 1, 0); PG8_STAGE(PG8_SA(0, 1), a2 + hstep, voffA);
;             PG8_WAIT_V(8); PG8_WAIT_L(0); PG8_BAR; PG8_MMA(0, 0, At, B0); PG8_MMA(0, 1, At, B1); PG8_BAR; PG8_SCHED;
	s_waitcnt lgkmcnt(0)
	v_mfma_f32_16x16x32_bf16 v[60:63], v[202:205], v[146:149], v[60:63]
	v_mfma_f32_16x16x32_bf16 v[56:59], v[202:205], v[178:181], v[56:59]
	v_mfma_f32_16x16x32_bf16 v[48:51], v[214:217], v[146:149], v[48:51]
	v_mfma_f32_16x16x32_bf16 v[40:43], v[214:217], v[178:181], v[40:43]
	v_mfma_f32_16x16x32_bf16 v[32:35], v[222:225], v[146:149], v[32:35]
	v_mfma_f32_16x16x32_bf16 v[24:27], v[222:225], v[178:181], v[24:27]
	v_mfma_f32_16x16x32_bf16 v[16:19], v[230:233], v[146:149], v[16:19]
	v_mfma_f32_16x16x32_bf16 v[8:11], v[230:233], v[178:181], v[8:11]
	v_mfma_f32_16x16x32_bf16 v[60:63], v[210:213], v[150:153], v[60:63]
	v_mfma_f32_16x16x32_bf16 v[56:59], v[210:213], v[182:185], v[56:59]
	v_mfma_f32_16x16x32_bf16 v[48:51], v[218:221], v[150:153], v[48:51]
	v_mfma_f32_16x16x32_bf16 v[40:43], v[218:221], v[182:185], v[40:43]
	v_mfma_f32_16x16x32_bf16 v[32:35], v[226:229], v[150:153], v[32:35]
	v_mfma_f32_16x16x32_bf16 v[24:27], v[226:229], v[182:185], v[24:27]
	v_mfma_f32_16x16x32_bf16 v[16:19], v[234:237], v[150:153], v[16:19]
	v_mfma_f32_16x16x32_bf16 v[8:11], v[234:237], v[182:185], v[8:11]
	v_mfma_f32_16x16x32_bf16 v[52:55], v[202:205], v[186:189], v[52:55]
	v_mfma_f32_16x16x32_bf16 v[44:47], v[202:205], v[194:197], v[44:47]
	v_mfma_f32_16x16x32_bf16 v[36:39], v[214:217], v[186:189], v[36:39]
	v_mfma_f32_16x16x32_bf16 v[28:31], v[214:217], v[194:197], v[28:31]
	v_mfma_f32_16x16x32_bf16 v[20:23], v[222:225], v[186:189], v[20:23]
	v_mfma_f32_16x16x32_bf16 v[12:15], v[222:225], v[194:197], v[12:15]
	v_mfma_f32_16x16x32_bf16 v[4:7], v[230:233], v[186:189], v[4:7]
	v_mfma_f32_16x16x32_bf16 v[0:3], v[230:233], v[194:197], v[0:3]
	v_mfma_f32_16x16x32_bf16 v[52:55], v[210:213], v[190:193], v[52:55]
	v_mfma_f32_16x16x32_bf16 v[44:47], v[210:213], v[198:201], v[44:47]
	v_mfma_f32_16x16x32_bf16 v[36:39], v[218:221], v[190:193], v[36:39]
	v_mfma_f32_16x16x32_bf16 v[28:31], v[218:221], v[198:201], v[28:31]
	v_mfma_f32_16x16x32_bf16 v[20:23], v[226:229], v[190:193], v[20:23]
	v_mfma_f32_16x16x32_bf16 v[12:15], v[226:229], v[198:201], v[12:15]
	v_mfma_f32_16x16x32_bf16 v[4:7], v[234:237], v[190:193], v[4:7]
	v_mfma_f32_16x16x32_bf16 v[0:3], v[234:237], v[198:201], v[0:3]
	s_barrier
	s_add_i32 s0, 0, 0x18000
	v_add_u32_e32 v136, s0, v158
	s_add_i32 s1, 0, 0x1c000
	ds_read_b128 v[146:149], v136
	ds_read_b128 v[150:153], v136 offset:1024
	ds_read_b128 v[178:181], v136 offset:2048
	ds_read_b128 v[182:185], v136 offset:3072
	v_add_u32_e32 v136, s1, v158
	ds_read_b128 v[186:189], v136
	ds_read_b128 v[190:193], v136 offset:1024
	ds_read_b128 v[194:197], v136 offset:2048
	ds_read_b128 v[198:201], v136 offset:3072
	s_add_u32 s52, s52, 0x40000
	s_addc_u32 s53, s53, 0
	s_mov_b32 m0, s59
	v_lshl_add_u64 v[244:245], s[52:53], 0, v[134:135]
	ds_read_b128 v[202:205], v171 offset:32768
	ds_read_b128 v[210:213], v171 offset:33792
	ds_read_b128 v[214:217], v171 offset:34816
	ds_read_b128 v[218:221], v171 offset:35840
	ds_read_b128 v[222:225], v171 offset:36864
	ds_read_b128 v[226:229], v171 offset:37888
	ds_read_b128 v[230:233], v171 offset:38912
	ds_read_b128 v[234:237], v171 offset:39936
	global_load_lds_dwordx4 v[244:245], off
	v_lshl_add_u64 v[244:245], s[52:53], 0, v[130:131]
	s_mov_b32 m0, s60
	s_nop 0
	global_load_lds_dwordx4 v[244:245], off
	s_waitcnt vmcnt(8)
	s_waitcnt lgkmcnt(0)
	s_barrier
; #define PG8_STAGE(bufoff, gbase, voff) do { _Pragma("unroll") for (int _i = 0; _i < 2; ++_i) \
;         __builtin_amdgcn_global_load_lds((const unsigned*)((const char*)(gbase) + (voff)[_i]), (PG8_LAS unsigned*)(lds + (bufoff) + ldsw + _i * 8192), 16, 0, 0); } while (0)
; #define PG8_LDA(dst, b, h) do { _Pragma("unroll") for (int m = 0; m < 4; ++m) _Pragma("unroll") for (int k = 0; k < 2; ++k) dst[m][k] = *(const PG8_LAS bf16x8*)(lds + PG8_SA(b, h) + aoff + m * 2048 + k * 1024); } while (0)
; #define PG8_MMA(ai, bj, At, Bt) do { __builtin_amdgcn_s_setprio(1); _Pragma("unroll") for (int m = 0; m < 4; ++m) _Pragma("unroll") for (int n = 0; n < 2; ++n) _Pragma("unroll") for (int k = 0; k < 2; ++k) \
;         acc[ai][bj][m][n] = __builtin_amdgcn_mfma_f32_16x16x32_bf16(Bt[n][k], At[m][k], acc[ai][bj][m][n], 0, 0, 0); __builtin_amdgcn_s_setprio(0); } while (0)
; #define PG8_WAIT_V(n) asm volatile("s_waitcnt vmcnt(" #n ")" ::: "memory")
; #define PG8_WAIT_L(n) asm volatile("s_waitcnt lgkmcnt(" #n ")" ::: "memory")
; #define PG8_BAR __builtin_amdgcn_s_barrier()
; #define PG8_SCHED __builtin_amdgcn_sched_barrier(0)
; template <class Epi, class Sched, bool ALIGN_EPI = false, bool SP2 = false>
; __device__ __forceinline__ void gemm_phase(PG8_LAS unsigned char* lds, const Gemm g, const Sched& S, const Epi& E) {
;     ...
;             PG8_WAIT_V(8); PG8_WAIT_L(0); PG8_BAR; PG8_MMA(0, 0, At, B0); PG8_MMA(0, 1, At, B1); PG8_BAR; PG8_SCHED;
;             PG8_LDA(At, 1, 1); PG8_STAGE(PG8_SB(1, 0), b3, voffB); PG8_STAGE(PG8_SB(1, 1), b3 + hstep, voffB); PG8_STAGE(PG8_SA(1, 0), a3, voffA);
;             PG8_WAIT_V(8); PG8_WAIT_L(0); PG8_BAR; PG8_MMA(1, 0, At, B0); PG8_MMA(1, 1, At, B1); PG8_BAR; PG8_SCHED;
	s_waitcnt lgkmcnt(0)
	v_mfma_f32_16x16x32_bf16 v[124:127], v[202:205], v[146:149], v[124:127]
	v_mfma_f32_16x16x32_bf16 v[120:123], v[202:205], v[178:181], v[120:123]
	v_mfma_f32_16x16x32_bf16 v[112:115], v[214:217], v[146:149], v[112:115]
	v_mfma_f32_16x16x32_bf16 v[104:107], v[214:217], v[178:181], v[104:107]
	v_mfma_f32_16x16x32_bf16 v[96:99], v[222:225], v[146:149], v[96:99]
	v_mfma_f32_16x16x32_bf16 v[88:91], v[222:225], v[178:181], v[88:91]
	v_mfma_f32_16x16x32_bf16 v[80:83], v[230:233], v[146:149], v[80:83]
	v_mfma_f32_16x16x32_bf16 v[72:75], v[230:233], v[178:181], v[72:75]
	v_mfma_f32_16x16x32_bf16 v[124:127], v[210:213], v[150:153], v[124:127]
	v_mfma_f32_16x16x32_bf16 v[120:123], v[210:213], v[182:185], v[120:123]
	v_mfma_f32_16x16x32_bf16 v[112:115], v[218:221], v[150:153], v[112:115]
	v_mfma_f32_16x16x32_bf16 v[104:107], v[218:221], v[182:185], v[104:107]
	v_mfma_f32_16x16x32_bf16 v[96:99], v[226:229], v[150:153], v[96:99]
	v_mfma_f32_16x16x32_bf16 v[88:91], v[226:229], v[182:185], v[88:91]
	v_mfma_f32_16x16x32_bf16 v[80:83], v[234:237], v[150:153], v[80:83]
	v_mfma_f32_16x16x32_bf16 v[72:75], v[234:237], v[182:185], v[72:75]
	v_mfma_f32_16x16x32_bf16 v[116:119], v[202:205], v[186:189], v[116:119]
	v_mfma_f32_16x16x32_bf16 v[108:111], v[202:205], v[194:197], v[108:111]
	ds_read_b128 v[202:205], v171 offset:49152
	v_mfma_f32_16x16x32_bf16 v[100:103], v[214:217], v[186:189], v[100:103]
	v_mfma_f32_16x16x32_bf16 v[92:95], v[214:217], v[194:197], v[92:95]
	ds_read_b128 v[214:217], v171 offset:51200
	v_mfma_f32_16x16x32_bf16 v[84:87], v[222:225], v[186:189], v[84:87]
	v_mfma_f32_16x16x32_bf16 v[76:79], v[222:225], v[194:197], v[76:79]
	ds_read_b128 v[222:225], v171 offset:53248
	v_mfma_f32_16x16x32_bf16 v[68:71], v[230:233], v[186:189], v[68:71]
	v_mfma_f32_16x16x32_bf16 v[64:67], v[230:233], v[194:197], v[64:67]
	ds_read_b128 v[230:233], v171 offset:55296
	v_mfma_f32_16x16x32_bf16 v[116:119], v[210:213], v[190:193], v[116:119]
	v_mfma_f32_16x16x32_bf16 v[108:111], v[210:213], v[198:201], v[108:111]
	ds_read_b128 v[210:213], v171 offset:50176
	v_mfma_f32_16x16x32_bf16 v[100:103], v[218:221], v[190:193], v[100:103]
	v_mfma_f32_16x16x32_bf16 v[92:95], v[218:221], v[198:201], v[92:95]
	ds_read_b128 v[218:221], v171 offset:52224
	v_mfma_f32_16x16x32_bf16 v[84:87], v[226:229], v[190:193], v[84:87]
	v_mfma_f32_16x16x32_bf16 v[76:79], v[226:229], v[198:201], v[76:79]
	ds_read_b128 v[226:229], v171 offset:54272
	v_mfma_f32_16x16x32_bf16 v[68:71], v[234:237], v[190:193], v[68:71]
	v_mfma_f32_16x16x32_bf16 v[64:67], v[234:237], v[198:201], v[64:67]
	ds_read_b128 v[234:237], v171 offset:56320
	s_barrier
	s_add_i32 s0, s0, s29
	v_lshl_add_u64 v[206:207], v[206:207], 0, s[38:39]
	s_mov_b32 m0, s0
	global_load_lds_dwordx4 v[206:207], off
	s_add_i32 m0, s0, 0x2000
	s_add_u32 s50, s50, 0x40080
	v_lshl_add_u64 v[206:207], v[238:239], 0, s[38:39]
	s_addc_u32 s51, s51, 0
	s_add_i32 s0, s1, s29
	global_load_lds_dwordx4 v[206:207], off
	v_lshl_add_u64 v[206:207], s[50:51], 0, v[132:133]
	s_mov_b32 m0, s0
	s_nop 0
	global_load_lds_dwordx4 v[206:207], off
	v_lshl_add_u64 v[206:207], s[50:51], 0, v[128:129]
	s_add_i32 m0, s0, 0x2000
	s_nop 0
	global_load_lds_dwordx4 v[206:207], off
	v_lshl_add_u64 v[206:207], v[240:241], 0, s[38:39]
	s_mov_b32 m0, s69
	s_nop 0
	global_load_lds_dwordx4 v[206:207], off
	v_lshl_add_u64 v[206:207], v[242:243], 0, s[38:39]
	s_mov_b32 m0, s70
	s_nop 0
	global_load_lds_dwordx4 v[206:207], off
	s_waitcnt vmcnt(8)
	s_waitcnt lgkmcnt(0)
	s_barrier
	s_waitcnt lgkmcnt(0)
	v_mfma_f32_16x16x32_bf16 v[60:63], v[202:205], v[146:149], v[60:63]
	v_mfma_f32_16x16x32_bf16 v[56:59], v[202:205], v[178:181], v[56:59]
	v_mfma_f32_16x16x32_bf16 v[48:51], v[214:217], v[146:149], v[48:51]
	v_mfma_f32_16x16x32_bf16 v[40:43], v[214:217], v[178:181], v[40:43]
	v_mfma_f32_16x16x32_bf16 v[32:35], v[222:225], v[146:149], v[32:35]
	v_mfma_f32_16x16x32_bf16 v[24:27], v[222:225], v[178:181], v[24:27]
	v_mfma_f32_16x16x32_bf16 v[16:19], v[230:233], v[146:149], v[16:19]
	v_mfma_f32_16x16x32_bf16 v[8:11], v[230:233], v[178:181], v[8:11]
	v_mfma_f32_16x16x32_bf16 v[60:63], v[210:213], v[150:153], v[60:63]
	v_mfma_f32_16x16x32_bf16 v[56:59], v[210:213], v[182:185], v[56:59]
	v_mfma_f32_16x16x32_bf16 v[48:51], v[218:221], v[150:153], v[48:51]
	v_mfma_f32_16x16x32_bf16 v[40:43], v[218:221], v[182:185], v[40:43]
	v_mfma_f32_16x16x32_bf16 v[32:35], v[226:229], v[150:153], v[32:35]
	v_mfma_f32_16x16x32_bf16 v[24:27], v[226:229], v[182:185], v[24:27]
	v_mfma_f32_16x16x32_bf16 v[16:19], v[234:237], v[150:153], v[16:19]
	v_mfma_f32_16x16x32_bf16 v[8:11], v[234:237], v[182:185], v[8:11]
	v_mfma_f32_16x16x32_bf16 v[52:55], v[202:205], v[186:189], v[52:55]
	v_mfma_f32_16x16x32_bf16 v[44:47], v[202:205], v[194:197], v[44:47]
	v_mfma_f32_16x16x32_bf16 v[36:39], v[214:217], v[186:189], v[36:39]
	v_mfma_f32_16x16x32_bf16 v[28:31], v[214:217], v[194:197], v[28:31]
	v_mfma_f32_16x16x32_bf16 v[20:23], v[222:225], v[186:189], v[20:23]
	v_mfma_f32_16x16x32_bf16 v[12:15], v[222:225], v[194:197], v[12:15]
	v_mfma_f32_16x16x32_bf16 v[4:7], v[230:233], v[186:189], v[4:7]
	v_mfma_f32_16x16x32_bf16 v[0:3], v[230:233], v[194:197], v[0:3]
	v_mfma_f32_16x16x32_bf16 v[52:55], v[210:213], v[190:193], v[52:55]
	v_mfma_f32_16x16x32_bf16 v[44:47], v[210:213], v[198:201], v[44:47]
	v_mfma_f32_16x16x32_bf16 v[36:39], v[218:221], v[190:193], v[36:39]
	v_mfma_f32_16x16x32_bf16 v[28:31], v[218:221], v[198:201], v[28:31]
	v_mfma_f32_16x16x32_bf16 v[20:23], v[226:229], v[190:193], v[20:23]
	v_mfma_f32_16x16x32_bf16 v[12:15], v[226:229], v[198:201], v[12:15]
	v_mfma_f32_16x16x32_bf16 v[4:7], v[234:237], v[190:193], v[4:7]
	v_mfma_f32_16x16x32_bf16 v[0:3], v[234:237], v[198:201], v[0:3]
	s_barrier
	s_add_i32 s93, s93, 2
	s_add_u32 s14, s14, 0x100
	s_addc_u32 s15, s15, 0
	s_add_u32 s91, s91, 0x100
	s_addc_u32 s92, s92, 0
	s_cmp_gt_u32 s93, 13
	s_cbranch_scc0 .Lp2_vloop
	s_branch .Lp2_kexit

; #define PG8_STAGE(bufoff, gbase, voff) do { _Pragma("unroll") for (int _i = 0; _i < 2; ++_i) \
;         __builtin_amdgcn_global_load_lds((const unsigned*)((const char*)(gbase) + (voff)[_i]), (PG8_LAS unsigned*)(lds + (bufoff) + ldsw + _i * 8192), 16, 0, 0); } while (0)
; #define PG8_LDA(dst, b, h) do { _Pragma("unroll") for (int m = 0; m < 4; ++m) _Pragma("unroll") for (int k = 0; k < 2; ++k) dst[m][k] = *(const PG8_LAS bf16x8*)(lds + PG8_SA(b, h) + aoff + m * 2048 + k * 1024); } while (0)
; #define PG8_LDB(dst, b, h) do { _Pragma("unroll") for (int n = 0; n < 2; ++n) _Pragma("unroll") for (int k = 0; k < 2; ++k) dst[n][k] = *(const PG8_LAS bf16x8*)(lds + PG8_SB(b, h) + boff + n * 2048 + k * 1024); } while (0)
; #define PG8_MMA(ai, bj, At, Bt) do { __builtin_amdgcn_s_setprio(1); _Pragma("unroll") for (int m = 0; m < 4; ++m) _Pragma("unroll") for (int n = 0; n < 2; ++n) _Pragma("unroll") for (int k = 0; k < 2; ++k) \
;         acc[ai][bj][m][n] = __builtin_amdgcn_mfma_f32_16x16x32_bf16(Bt[n][k], At[m][k], acc[ai][bj][m][n], 0, 0, 0); __builtin_amdgcn_s_setprio(0); } while (0)
; #define PG8_WAIT_V(n) asm volatile("s_waitcnt vmcnt(" #n ")" ::: "memory")
; #define PG8_WAIT_L(n) asm volatile("s_waitcnt lgkmcnt(" #n ")" ::: "memory")
; template <class Epi, class Sched, bool ALIGN_EPI = false, bool SP2 = false>
; __device__ __forceinline__ void gemm_phase(PG8_LAS unsigned char* lds, const Gemm g, const Sched& S, const Epi& E) {
;     ...
;             const bool last = (t == nt - 2);
;             const char* a1 = cA + (size_t)(t + 1) * kstep;
;             const char* a2 = last ? nA : cA + (size_t)(t + 2) * kstep; const char* b2 = last ? nB : cB + (size_t)(t + 2) * kstep;
;             const char* a3 = a2 + kstep; const char* b3 = b2 + kstep;
;             if (last && has_next) S.a_ready(nxt);
;             if constexpr (SP2) {
;             PG8_LDB(B0, 0, 0); PG8_LDB(B1, 0, 1); PG8_SCHED; PG8_LDA(At, 0, 0); PG8_STAGE(PG8_SA(1, 1), a1 + hstep, voffA);
;             PG8_WAIT_V(8); PG8_WAIT_L(0); PG8_BAR; PG8_MMA(0, 0, At, B0); PG8_MMA(0, 1, At, B1); PG8_BAR; PG8_SCHED;
;             PG8_LDA(At, 0, 1); PG8_STAGE(PG8_SB(0, 0), b2, voffB); PG8_STAGE(PG8_SB(0, 1), b2 + hstep, voffB); PG8_STAGE(PG8_SA(0, 0), a2, voffA);
;             PG8_WAIT_V(8); PG8_WAIT_L(0); PG8_BAR; PG8_MMA(1, 0, At, B0); PG8_MMA(1, 1, At, B1); PG8_BAR; PG8_SCHED;
.Lprio4_done:
.LBB0_458:
	ds_read_b128 v[64:67], v249
	ds_read_b128 v[68:71], v249 offset:1024
	ds_read_b128 v[76:79], v249 offset:2048
	ds_read_b128 v[80:83], v249 offset:3072
	ds_read_b128 v[144:147], v250
	ds_read_b128 v[148:151], v250 offset:1024
	ds_read_b128 v[152:155], v250 offset:2048
	ds_read_b128 v[156:159], v250 offset:3072
	s_add_u32 s0, s54, 0xfffc0080
	s_addc_u32 s1, s55, -1
	s_cmp_eq_u32 s77, 12
	s_cselect_b32 s59, s15, s1
	s_cselect_b32 s58, s23, s0
	s_cselect_b32 s57, s47, s76
	s_cselect_b32 s56, s49, s75
	v_lshl_add_u64 v[192:193], s[54:55], 0, v[220:221]
	s_add_i32 m0, s28, 0xc000
	ds_read_b128 v[160:163], v251
	ds_read_b128 v[164:167], v251 offset:1024
	ds_read_b128 v[168:171], v251 offset:2048
	ds_read_b128 v[172:175], v251 offset:3072
	ds_read_b128 v[176:179], v251 offset:4096
	ds_read_b128 v[180:183], v251 offset:5120
	ds_read_b128 v[184:187], v251 offset:6144
	ds_read_b128 v[188:191], v251 offset:7168
	global_load_lds_dwordx4 v[192:193], off
	v_lshl_add_u64 v[192:193], s[54:55], 0, v[222:223]
	s_add_i32 m0, s28, 0xe000
	s_nop 0
	global_load_lds_dwordx4 v[192:193], off
	s_waitcnt vmcnt(8)
	s_waitcnt lgkmcnt(0)
	s_barrier
	s_waitcnt lgkmcnt(0)
	v_mfma_f32_16x16x32_bf16 v[140:143], v[64:67], v[160:163], v[140:143]
	v_mfma_f32_16x16x32_bf16 v[136:139], v[76:79], v[160:163], v[136:139]
	v_mfma_f32_16x16x32_bf16 v[124:127], v[64:67], v[168:171], v[124:127]
	v_mfma_f32_16x16x32_bf16 v[120:123], v[76:79], v[168:171], v[120:123]
	v_mfma_f32_16x16x32_bf16 v[108:111], v[64:67], v[176:179], v[108:111]
	v_mfma_f32_16x16x32_bf16 v[104:107], v[76:79], v[176:179], v[104:107]
	v_mfma_f32_16x16x32_bf16 v[92:95], v[64:67], v[184:187], v[92:95]
	v_mfma_f32_16x16x32_bf16 v[88:91], v[76:79], v[184:187], v[88:91]
	v_mfma_f32_16x16x32_bf16 v[140:143], v[68:71], v[164:167], v[140:143]
	v_mfma_f32_16x16x32_bf16 v[136:139], v[80:83], v[164:167], v[136:139]
	v_mfma_f32_16x16x32_bf16 v[124:127], v[68:71], v[172:175], v[124:127]
	v_mfma_f32_16x16x32_bf16 v[120:123], v[80:83], v[172:175], v[120:123]
	v_mfma_f32_16x16x32_bf16 v[108:111], v[68:71], v[180:183], v[108:111]
	v_mfma_f32_16x16x32_bf16 v[104:107], v[80:83], v[180:183], v[104:107]
	v_mfma_f32_16x16x32_bf16 v[92:95], v[68:71], v[188:191], v[92:95]
	v_mfma_f32_16x16x32_bf16 v[88:91], v[80:83], v[188:191], v[88:91]
	v_mfma_f32_16x16x32_bf16 v[132:135], v[144:147], v[160:163], v[132:135]
	v_mfma_f32_16x16x32_bf16 v[128:131], v[152:155], v[160:163], v[128:131]
	ds_read_b128 v[160:163], v251 offset:16384
	v_mfma_f32_16x16x32_bf16 v[116:119], v[144:147], v[168:171], v[116:119]
	v_mfma_f32_16x16x32_bf16 v[112:115], v[152:155], v[168:171], v[112:115]
	ds_read_b128 v[168:171], v251 offset:18432
	v_mfma_f32_16x16x32_bf16 v[100:103], v[144:147], v[176:179], v[100:103]
	v_mfma_f32_16x16x32_bf16 v[96:99], v[152:155], v[176:179], v[96:99]
	ds_read_b128 v[176:179], v251 offset:20480
	v_mfma_f32_16x16x32_bf16 v[84:87], v[144:147], v[184:187], v[84:87]
	v_mfma_f32_16x16x32_bf16 v[72:75], v[152:155], v[184:187], v[72:75]
	ds_read_b128 v[184:187], v251 offset:22528
	v_mfma_f32_16x16x32_bf16 v[132:135], v[148:151], v[164:167], v[132:135]
	v_mfma_f32_16x16x32_bf16 v[128:131], v[156:159], v[164:167], v[128:131]
	ds_read_b128 v[164:167], v251 offset:17408
	v_mfma_f32_16x16x32_bf16 v[116:119], v[148:151], v[172:175], v[116:119]
	v_mfma_f32_16x16x32_bf16 v[112:115], v[156:159], v[172:175], v[112:115]
	ds_read_b128 v[172:175], v251 offset:19456
	v_mfma_f32_16x16x32_bf16 v[100:103], v[148:151], v[180:183], v[100:103]
	v_mfma_f32_16x16x32_bf16 v[96:99], v[156:159], v[180:183], v[96:99]
	ds_read_b128 v[180:183], v251 offset:21504
	v_mfma_f32_16x16x32_bf16 v[84:87], v[148:151], v[188:191], v[84:87]
	v_mfma_f32_16x16x32_bf16 v[72:75], v[156:159], v[188:191], v[72:75]
	ds_read_b128 v[188:191], v251 offset:23552
	s_barrier
	s_add_i32 s0, s70, s7
	v_lshl_add_u64 v[192:193], s[56:57], 0, v[212:213]
	s_mov_b32 m0, s0
	global_load_lds_dwordx4 v[192:193], off
	s_add_i32 m0, s0, 0x2000
	s_add_u32 s78, s56, 0x40000
	v_lshl_add_u64 v[194:195], s[56:57], 0, v[216:217]
	s_addc_u32 s79, s57, 0
	s_add_i32 s0, s71, s7
	global_load_lds_dwordx4 v[194:195], off
	v_lshl_add_u64 v[196:197], s[78:79], 0, v[212:213]
	s_mov_b32 m0, s0
	v_lshl_add_u64 v[198:199], s[58:59], 0, v[214:215]
	global_load_lds_dwordx4 v[196:197], off
	v_lshl_add_u64 v[196:197], s[78:79], 0, v[216:217]
	s_add_i32 m0, s0, 0x2000
	s_nop 0
	global_load_lds_dwordx4 v[196:197], off
	v_lshl_add_u64 v[196:197], s[58:59], 0, v[210:211]
	s_mov_b32 m0, s28
	s_nop 0
	global_load_lds_dwordx4 v[196:197], off
	s_mov_b32 m0, s29
	s_nop 0
	global_load_lds_dwordx4 v[198:199], off
	s_waitcnt vmcnt(8)
	s_waitcnt lgkmcnt(0)
	s_barrier
; #define PG8_STAGE(bufoff, gbase, voff) do { _Pragma("unroll") for (int _i = 0; _i < 2; ++_i) \
;         __builtin_amdgcn_global_load_lds((const unsigned*)((const char*)(gbase) + (voff)[_i]), (PG8_LAS unsigned*)(lds + (bufoff) + ldsw + _i * 8192), 16, 0, 0); } while (0)
; #define PG8_LDA(dst, b, h) do { _Pragma("unroll") for (int m = 0; m < 4; ++m) _Pragma("unroll") for (int k = 0; k < 2; ++k) dst[m][k] = *(const PG8_LAS bf16x8*)(lds + PG8_SA(b, h) + aoff + m * 2048 + k * 1024); } while (0)
; #define PG8_LDB(dst, b, h) do { _Pragma("unroll") for (int n = 0; n < 2; ++n) _Pragma("unroll") for (int k = 0; k < 2; ++k) dst[n][k] = *(const PG8_LAS bf16x8*)(lds + PG8_SB(b, h) + boff + n * 2048 + k * 1024); } while (0)
; #define PG8_MMA(ai, bj, At, Bt) do { __builtin_amdgcn_s_setprio(1); _Pragma("unroll") for (int m = 0; m < 4; ++m) _Pragma("unroll") for (int n = 0; n < 2; ++n) _Pragma("unroll") for (int k = 0; k < 2; ++k) \
;         acc[ai][bj][m][n] = __builtin_amdgcn_mfma_f32_16x16x32_bf16(Bt[n][k], At[m][k], acc[ai][bj][m][n], 0, 0, 0); __builtin_amdgcn_s_setprio(0); } while (0)
; #define PG8_WAIT_V(n) asm volatile("s_waitcnt vmcnt(" #n ")" ::: "memory")
; #define PG8_WAIT_L(n) asm volatile("s_waitcnt lgkmcnt(" #n ")" ::: "memory")
; #define PG8_BAR __builtin_amdgcn_s_barrier()
; #define PG8_SCHED __builtin_amdgcn_sched_barrier(0)
; template <class Epi, class Sched, bool ALIGN_EPI = false, bool SP2 = false>
; __device__ __forceinline__ void gemm_phase(PG8_LAS unsigned char* lds, const Gemm g, const Sched& S, const Epi& E) {
;     ...
;             PG8_WAIT_V(8); PG8_WAIT_L(0); PG8_BAR; PG8_MMA(1, 0, At, B0); PG8_MMA(1, 1, At, B1); PG8_BAR; PG8_SCHED;
;             PG8_LDB(B0, 1, 0); PG8_LDB(B1, 1, 1); PG8_SCHED; PG8_LDA(At, 1, 0); PG8_STAGE(PG8_SA(0, 1), a2 + hstep, voffA);
;             PG8_WAIT_V(8); PG8_WAIT_L(0); PG8_BAR; PG8_MMA(0, 0, At, B0); PG8_MMA(0, 1, At, B1); PG8_BAR; PG8_SCHED;
;             PG8_LDA(At, 1, 1); PG8_STAGE(PG8_SB(1, 0), b3, voffB); PG8_STAGE(PG8_SB(1, 1), b3 + hstep, voffB); PG8_STAGE(PG8_SA(1, 0), a3, voffA);
	s_waitcnt lgkmcnt(0)
	v_mfma_f32_16x16x32_bf16 v[60:63], v[64:67], v[160:163], v[60:63]
	v_mfma_f32_16x16x32_bf16 v[56:59], v[76:79], v[160:163], v[56:59]
	v_mfma_f32_16x16x32_bf16 v[44:47], v[64:67], v[168:171], v[44:47]
	v_mfma_f32_16x16x32_bf16 v[40:43], v[76:79], v[168:171], v[40:43]
	v_mfma_f32_16x16x32_bf16 v[28:31], v[64:67], v[176:179], v[28:31]
	v_mfma_f32_16x16x32_bf16 v[24:27], v[76:79], v[176:179], v[24:27]
	v_mfma_f32_16x16x32_bf16 v[12:15], v[64:67], v[184:187], v[12:15]
	v_mfma_f32_16x16x32_bf16 v[8:11], v[76:79], v[184:187], v[8:11]
	v_mfma_f32_16x16x32_bf16 v[60:63], v[68:71], v[164:167], v[60:63]
	v_mfma_f32_16x16x32_bf16 v[56:59], v[80:83], v[164:167], v[56:59]
	v_mfma_f32_16x16x32_bf16 v[44:47], v[68:71], v[172:175], v[44:47]
	v_mfma_f32_16x16x32_bf16 v[40:43], v[80:83], v[172:175], v[40:43]
	v_mfma_f32_16x16x32_bf16 v[28:31], v[68:71], v[180:183], v[28:31]
	v_mfma_f32_16x16x32_bf16 v[24:27], v[80:83], v[180:183], v[24:27]
	v_mfma_f32_16x16x32_bf16 v[12:15], v[68:71], v[188:191], v[12:15]
	v_mfma_f32_16x16x32_bf16 v[8:11], v[80:83], v[188:191], v[8:11]
	v_mfma_f32_16x16x32_bf16 v[52:55], v[144:147], v[160:163], v[52:55]
	v_mfma_f32_16x16x32_bf16 v[48:51], v[152:155], v[160:163], v[48:51]
	v_mfma_f32_16x16x32_bf16 v[36:39], v[144:147], v[168:171], v[36:39]
	v_mfma_f32_16x16x32_bf16 v[32:35], v[152:155], v[168:171], v[32:35]
	v_mfma_f32_16x16x32_bf16 v[20:23], v[144:147], v[176:179], v[20:23]
	v_mfma_f32_16x16x32_bf16 v[16:19], v[152:155], v[176:179], v[16:19]
	v_mfma_f32_16x16x32_bf16 v[4:7], v[144:147], v[184:187], v[4:7]
	v_mfma_f32_16x16x32_bf16 v[0:3], v[152:155], v[184:187], v[0:3]
	v_mfma_f32_16x16x32_bf16 v[52:55], v[148:151], v[164:167], v[52:55]
	v_mfma_f32_16x16x32_bf16 v[48:51], v[156:159], v[164:167], v[48:51]
	v_mfma_f32_16x16x32_bf16 v[36:39], v[148:151], v[172:175], v[36:39]
	v_mfma_f32_16x16x32_bf16 v[32:35], v[156:159], v[172:175], v[32:35]
	v_mfma_f32_16x16x32_bf16 v[20:23], v[148:151], v[180:183], v[20:23]
	v_mfma_f32_16x16x32_bf16 v[16:19], v[156:159], v[180:183], v[16:19]
	v_mfma_f32_16x16x32_bf16 v[4:7], v[148:151], v[188:191], v[4:7]
	v_mfma_f32_16x16x32_bf16 v[0:3], v[156:159], v[188:191], v[0:3]
	s_barrier
	s_add_i32 s0, 0, 0x18000
	s_add_i32 s1, 0, 0x1c000
	v_add_u32_e32 v80, s0, v247
	v_add_u32_e32 v156, s1, v247
	ds_read_b128 v[64:67], v80
	ds_read_b128 v[68:71], v80 offset:1024
	ds_read_b128 v[76:79], v80 offset:2048
	ds_read_b128 v[80:83], v80 offset:3072
	ds_read_b128 v[144:147], v156
	ds_read_b128 v[148:151], v156 offset:1024
	ds_read_b128 v[152:155], v156 offset:2048
	ds_read_b128 v[156:159], v156 offset:3072
	s_add_u32 s58, s58, 0x40000
	s_addc_u32 s59, s59, 0
	s_mov_b32 m0, s60
	v_lshl_add_u64 v[200:201], s[58:59], 0, v[210:211]
	ds_read_b128 v[160:163], v251 offset:32768
	ds_read_b128 v[164:167], v251 offset:33792
	ds_read_b128 v[168:171], v251 offset:34816
	ds_read_b128 v[172:175], v251 offset:35840
	ds_read_b128 v[176:179], v251 offset:36864
	ds_read_b128 v[180:183], v251 offset:37888
	ds_read_b128 v[184:187], v251 offset:38912
	ds_read_b128 v[188:191], v251 offset:39936
	global_load_lds_dwordx4 v[200:201], off
	v_lshl_add_u64 v[200:201], s[58:59], 0, v[214:215]
	s_mov_b32 m0, s61
	s_nop 0
	global_load_lds_dwordx4 v[200:201], off
	s_waitcnt vmcnt(8)
	s_waitcnt lgkmcnt(0)
	s_barrier
	s_waitcnt lgkmcnt(0)
	v_mfma_f32_16x16x32_bf16 v[140:143], v[64:67], v[160:163], v[140:143]
	v_mfma_f32_16x16x32_bf16 v[136:139], v[76:79], v[160:163], v[136:139]
	v_mfma_f32_16x16x32_bf16 v[124:127], v[64:67], v[168:171], v[124:127]
	v_mfma_f32_16x16x32_bf16 v[120:123], v[76:79], v[168:171], v[120:123]
	v_mfma_f32_16x16x32_bf16 v[108:111], v[64:67], v[176:179], v[108:111]
	v_mfma_f32_16x16x32_bf16 v[104:107], v[76:79], v[176:179], v[104:107]
	v_mfma_f32_16x16x32_bf16 v[92:95], v[64:67], v[184:187], v[92:95]
	v_mfma_f32_16x16x32_bf16 v[88:91], v[76:79], v[184:187], v[88:91]
	v_mfma_f32_16x16x32_bf16 v[140:143], v[68:71], v[164:167], v[140:143]
	v_mfma_f32_16x16x32_bf16 v[136:139], v[80:83], v[164:167], v[136:139]
	v_mfma_f32_16x16x32_bf16 v[124:127], v[68:71], v[172:175], v[124:127]
	v_mfma_f32_16x16x32_bf16 v[120:123], v[80:83], v[172:175], v[120:123]
	v_mfma_f32_16x16x32_bf16 v[108:111], v[68:71], v[180:183], v[108:111]
	v_mfma_f32_16x16x32_bf16 v[104:107], v[80:83], v[180:183], v[104:107]
	v_mfma_f32_16x16x32_bf16 v[92:95], v[68:71], v[188:191], v[92:95]
	v_mfma_f32_16x16x32_bf16 v[88:91], v[80:83], v[188:191], v[88:91]
	v_mfma_f32_16x16x32_bf16 v[132:135], v[144:147], v[160:163], v[132:135]
	v_mfma_f32_16x16x32_bf16 v[128:131], v[152:155], v[160:163], v[128:131]
	ds_read_b128 v[160:163], v251 offset:49152
	v_mfma_f32_16x16x32_bf16 v[116:119], v[144:147], v[168:171], v[116:119]
	v_mfma_f32_16x16x32_bf16 v[112:115], v[152:155], v[168:171], v[112:115]
	ds_read_b128 v[168:171], v251 offset:51200
	v_mfma_f32_16x16x32_bf16 v[100:103], v[144:147], v[176:179], v[100:103]
	v_mfma_f32_16x16x32_bf16 v[96:99], v[152:155], v[176:179], v[96:99]
	ds_read_b128 v[176:179], v251 offset:53248
	v_mfma_f32_16x16x32_bf16 v[84:87], v[144:147], v[184:187], v[84:87]
	v_mfma_f32_16x16x32_bf16 v[72:75], v[152:155], v[184:187], v[72:75]
	ds_read_b128 v[184:187], v251 offset:55296
	v_mfma_f32_16x16x32_bf16 v[132:135], v[148:151], v[164:167], v[132:135]
	v_mfma_f32_16x16x32_bf16 v[128:131], v[156:159], v[164:167], v[128:131]
	ds_read_b128 v[164:167], v251 offset:50176
	v_mfma_f32_16x16x32_bf16 v[116:119], v[148:151], v[172:175], v[116:119]
	v_mfma_f32_16x16x32_bf16 v[112:115], v[156:159], v[172:175], v[112:115]
	ds_read_b128 v[172:175], v251 offset:52224
	v_mfma_f32_16x16x32_bf16 v[100:103], v[148:151], v[180:183], v[100:103]
	v_mfma_f32_16x16x32_bf16 v[96:99], v[156:159], v[180:183], v[96:99]
	ds_read_b128 v[180:183], v251 offset:54272
	v_mfma_f32_16x16x32_bf16 v[84:87], v[148:151], v[188:191], v[84:87]
	v_mfma_f32_16x16x32_bf16 v[72:75], v[156:159], v[188:191], v[72:75]
	ds_read_b128 v[188:191], v251 offset:56320
	s_barrier
; #define PG8_STAGE(bufoff, gbase, voff) do { _Pragma("unroll") for (int _i = 0; _i < 2; ++_i) \
;         __builtin_amdgcn_global_load_lds((const unsigned*)((const char*)(gbase) + (voff)[_i]), (PG8_LAS unsigned*)(lds + (bufoff) + ldsw + _i * 8192), 16, 0, 0); } while (0)
; #define PG8_LDA(dst, b, h) do { _Pragma("unroll") for (int m = 0; m < 4; ++m) _Pragma("unroll") for (int k = 0; k < 2; ++k) dst[m][k] = *(const PG8_LAS bf16x8*)(lds + PG8_SA(b, h) + aoff + m * 2048 + k * 1024); } while (0)
; #define PG8_MMA(ai, bj, At, Bt) do { __builtin_amdgcn_s_setprio(1); _Pragma("unroll") for (int m = 0; m < 4; ++m) _Pragma("unroll") for (int n = 0; n < 2; ++n) _Pragma("unroll") for (int k = 0; k < 2; ++k) \
;         acc[ai][bj][m][n] = __builtin_amdgcn_mfma_f32_16x16x32_bf16(Bt[n][k], At[m][k], acc[ai][bj][m][n], 0, 0, 0); __builtin_amdgcn_s_setprio(0); } while (0)
; #define PG8_WAIT_V(n) asm volatile("s_waitcnt vmcnt(" #n ")" ::: "memory")
; #define PG8_WAIT_L(n) asm volatile("s_waitcnt lgkmcnt(" #n ")" ::: "memory")
; #define PG8_BAR __builtin_amdgcn_s_barrier()
; #define PG8_SCHED __builtin_amdgcn_sched_barrier(0)
; template <class Epi, class Sched, bool ALIGN_EPI = false, bool SP2 = false>
; __device__ __forceinline__ void gemm_phase(PG8_LAS unsigned char* lds, const Gemm g, const Sched& S, const Epi& E) {
;     ...
;             PG8_LDA(At, 1, 1); PG8_STAGE(PG8_SB(1, 0), b3, voffB); PG8_STAGE(PG8_SB(1, 1), b3 + hstep, voffB); PG8_STAGE(PG8_SA(1, 0), a3, voffA);
;             PG8_WAIT_V(8); PG8_WAIT_L(0); PG8_BAR; PG8_MMA(1, 0, At, B0); PG8_MMA(1, 1, At, B1); PG8_BAR; PG8_SCHED;
	s_add_i32 s0, s0, s7
	v_lshl_add_u64 v[192:193], v[192:193], 0, s[42:43]
	s_mov_b32 m0, s0
	global_load_lds_dwordx4 v[192:193], off
	s_add_i32 m0, s0, 0x2000
	s_add_u32 s56, s56, 0x40080
	v_lshl_add_u64 v[192:193], v[194:195], 0, s[42:43]
	s_addc_u32 s57, s57, 0
	s_add_i32 s0, s1, s7
	global_load_lds_dwordx4 v[192:193], off
	v_lshl_add_u64 v[192:193], s[56:57], 0, v[212:213]
	s_mov_b32 m0, s0
	s_nop 0
	global_load_lds_dwordx4 v[192:193], off
	v_lshl_add_u64 v[192:193], s[56:57], 0, v[216:217]
	s_add_i32 m0, s0, 0x2000
	s_nop 0
	global_load_lds_dwordx4 v[192:193], off
	v_lshl_add_u64 v[192:193], v[196:197], 0, s[42:43]
	s_mov_b32 m0, s65
	s_nop 0
	global_load_lds_dwordx4 v[192:193], off
	v_lshl_add_u64 v[192:193], v[198:199], 0, s[42:43]
	s_mov_b32 m0, s66
	s_nop 0
	global_load_lds_dwordx4 v[192:193], off
	s_waitcnt vmcnt(8)
	s_waitcnt lgkmcnt(0)
	s_barrier
	s_waitcnt lgkmcnt(0)
	v_mfma_f32_16x16x32_bf16 v[60:63], v[64:67], v[160:163], v[60:63]
	v_mfma_f32_16x16x32_bf16 v[56:59], v[76:79], v[160:163], v[56:59]
	v_mfma_f32_16x16x32_bf16 v[44:47], v[64:67], v[168:171], v[44:47]
	v_mfma_f32_16x16x32_bf16 v[40:43], v[76:79], v[168:171], v[40:43]
	v_mfma_f32_16x16x32_bf16 v[28:31], v[64:67], v[176:179], v[28:31]
	v_mfma_f32_16x16x32_bf16 v[24:27], v[76:79], v[176:179], v[24:27]
	v_mfma_f32_16x16x32_bf16 v[12:15], v[64:67], v[184:187], v[12:15]
	v_mfma_f32_16x16x32_bf16 v[8:11], v[76:79], v[184:187], v[8:11]
	v_mfma_f32_16x16x32_bf16 v[60:63], v[68:71], v[164:167], v[60:63]
	v_mfma_f32_16x16x32_bf16 v[56:59], v[80:83], v[164:167], v[56:59]
	v_mfma_f32_16x16x32_bf16 v[44:47], v[68:71], v[172:175], v[44:47]
	v_mfma_f32_16x16x32_bf16 v[40:43], v[80:83], v[172:175], v[40:43]
	v_mfma_f32_16x16x32_bf16 v[28:31], v[68:71], v[180:183], v[28:31]
	v_mfma_f32_16x16x32_bf16 v[24:27], v[80:83], v[180:183], v[24:27]
	v_mfma_f32_16x16x32_bf16 v[12:15], v[68:71], v[188:191], v[12:15]
	v_mfma_f32_16x16x32_bf16 v[8:11], v[80:83], v[188:191], v[8:11]
	v_mfma_f32_16x16x32_bf16 v[52:55], v[144:147], v[160:163], v[52:55]
	v_mfma_f32_16x16x32_bf16 v[48:51], v[152:155], v[160:163], v[48:51]
	v_mfma_f32_16x16x32_bf16 v[36:39], v[144:147], v[168:171], v[36:39]
	v_mfma_f32_16x16x32_bf16 v[32:35], v[152:155], v[168:171], v[32:35]
	v_mfma_f32_16x16x32_bf16 v[20:23], v[144:147], v[176:179], v[20:23]
	v_mfma_f32_16x16x32_bf16 v[16:19], v[152:155], v[176:179], v[16:19]
	v_mfma_f32_16x16x32_bf16 v[4:7], v[144:147], v[184:187], v[4:7]
	v_mfma_f32_16x16x32_bf16 v[0:3], v[152:155], v[184:187], v[0:3]
	v_mfma_f32_16x16x32_bf16 v[52:55], v[148:151], v[164:167], v[52:55]
	v_mfma_f32_16x16x32_bf16 v[48:51], v[156:159], v[164:167], v[48:51]
	v_mfma_f32_16x16x32_bf16 v[36:39], v[148:151], v[172:175], v[36:39]
	v_mfma_f32_16x16x32_bf16 v[32:35], v[156:159], v[172:175], v[32:35]
	v_mfma_f32_16x16x32_bf16 v[20:23], v[148:151], v[180:183], v[20:23]
	v_mfma_f32_16x16x32_bf16 v[16:19], v[156:159], v[180:183], v[16:19]
	v_mfma_f32_16x16x32_bf16 v[4:7], v[148:151], v[188:191], v[4:7]
	v_mfma_f32_16x16x32_bf16 v[0:3], v[156:159], v[188:191], v[0:3]
	s_barrier
	s_add_i32 s77, s77, 2
	s_add_u32 s54, s54, 0x100
	s_addc_u32 s55, s55, 0
	s_add_u32 s75, s75, 0x100
	s_addc_u32 s76, s76, 0
	s_cmp_gt_u32 s77, 13
	s_cbranch_scc0 .LBB0_458
	s_setprio 0
	s_and_b64 vcc, exec, s[44:45]
	s_cbranch_vccz .LBB0_461
	s_barrier

; #define PG8_STAGE(bufoff, gbase, voff) do { _Pragma("unroll") for (int _i = 0; _i < 2; ++_i) \
;         __builtin_amdgcn_global_load_lds((const unsigned*)((const char*)(gbase) + (voff)[_i]), (PG8_LAS unsigned*)(lds + (bufoff) + ldsw + _i * 8192), 16, 0, 0); } while (0)
; #define PG8_LDA(dst, b, h) do { _Pragma("unroll") for (int m = 0; m < 4; ++m) _Pragma("unroll") for (int k = 0; k < 2; ++k) dst[m][k] = *(const PG8_LAS bf16x8*)(lds + PG8_SA(b, h) + aoff + m * 2048 + k * 1024); } while (0)
; #define PG8_LDB(dst, b, h) do { _Pragma("unroll") for (int n = 0; n < 2; ++n) _Pragma("unroll") for (int k = 0; k < 2; ++k) dst[n][k] = *(const PG8_LAS bf16x8*)(lds + PG8_SB(b, h) + boff + n * 2048 + k * 1024); } while (0)
; #define PG8_MMA(ai, bj, At, Bt) do { __builtin_amdgcn_s_setprio(1); _Pragma("unroll") for (int m = 0; m < 4; ++m) _Pragma("unroll") for (int n = 0; n < 2; ++n) _Pragma("unroll") for (int k = 0; k < 2; ++k) \
;         acc[ai][bj][m][n] = __builtin_amdgcn_mfma_f32_16x16x32_bf16(Bt[n][k], At[m][k], acc[ai][bj][m][n], 0, 0, 0); __builtin_amdgcn_s_setprio(0); } while (0)
; #define PG8_WAIT_V(n) asm volatile("s_waitcnt vmcnt(" #n ")" ::: "memory")
; #define PG8_WAIT_L(n) asm volatile("s_waitcnt lgkmcnt(" #n ")" ::: "memory")
; template <class Epi, class Sched, bool ALIGN_EPI = false, bool SP2 = false>
; __device__ __forceinline__ void gemm_phase(PG8_LAS unsigned char* lds, const Gemm g, const Sched& S, const Epi& E) {
;     ...
;             const bool last = (t == nt - 2);
;             const char* a1 = cA + (size_t)(t + 1) * kstep;
;             const char* a2 = last ? nA : cA + (size_t)(t + 2) * kstep; const char* b2 = last ? nB : cB + (size_t)(t + 2) * kstep;
;             const char* a3 = a2 + kstep; const char* b3 = b2 + kstep;
;             if (last && has_next) S.a_ready(nxt);
;             if constexpr (SP2) {
;             PG8_LDB(B0, 0, 0); PG8_LDB(B1, 0, 1); PG8_SCHED; PG8_LDA(At, 0, 0); PG8_STAGE(PG8_SA(1, 1), a1 + hstep, voffA);
;             PG8_WAIT_V(8); PG8_WAIT_L(0); PG8_BAR; PG8_MMA(0, 0, At, B0); PG8_MMA(0, 1, At, B1); PG8_BAR; PG8_SCHED;
;             PG8_LDA(At, 0, 1); PG8_STAGE(PG8_SB(0, 0), b2, voffB); PG8_STAGE(PG8_SB(0, 1), b2 + hstep, voffB); PG8_STAGE(PG8_SA(0, 0), a2, voffA);
;             PG8_WAIT_V(8); PG8_WAIT_L(0); PG8_BAR; PG8_MMA(1, 0, At, B0); PG8_MMA(1, 1, At, B1); PG8_BAR; PG8_SCHED;
.Lprio7_done:
.LBB0_674:
	ds_read_b128 v[128:131], v171
	ds_read_b128 v[132:135], v171 offset:1024
	ds_read_b128 v[136:139], v171 offset:2048
	ds_read_b128 v[140:143], v171 offset:3072
	ds_read_b128 v[162:165], v172
	ds_read_b128 v[174:177], v172 offset:1024
	ds_read_b128 v[178:181], v172 offset:2048
	ds_read_b128 v[182:185], v172 offset:3072
	s_add_u32 s24, s22, 0xfff50080
	s_addc_u32 s25, s23, -1
	s_cmp_eq_u32 s52, 40
	s_cselect_b32 s29, s5, s25
	s_cselect_b32 s28, s4, s24
	s_cselect_b32 s25, s21, s51
	s_cselect_b32 s24, s20, s50
	v_lshl_add_u64 v[166:167], s[22:23], 0, v[154:155]
	s_add_i32 m0, s35, 0xc000
	ds_read_b128 v[186:189], v173
	ds_read_b128 v[190:193], v173 offset:1024
	ds_read_b128 v[194:197], v173 offset:2048
	ds_read_b128 v[198:201], v173 offset:3072
	ds_read_b128 v[202:205], v173 offset:4096
	ds_read_b128 v[206:209], v173 offset:5120
	ds_read_b128 v[210:213], v173 offset:6144
	ds_read_b128 v[214:217], v173 offset:7168
	global_load_lds_dwordx4 v[166:167], off
	v_lshl_add_u64 v[166:167], s[22:23], 0, v[156:157]
	s_add_i32 m0, s35, 0xe000
	s_nop 0
	global_load_lds_dwordx4 v[166:167], off
	s_waitcnt vmcnt(8)
	s_waitcnt lgkmcnt(0)
	s_barrier
	s_waitcnt lgkmcnt(0)
	v_mfma_f32_16x16x32_bf16 v[124:127], v[128:131], v[186:189], v[124:127]
	v_mfma_f32_16x16x32_bf16 v[120:123], v[136:139], v[186:189], v[120:123]
	v_mfma_f32_16x16x32_bf16 v[116:119], v[128:131], v[194:197], v[116:119]
	v_mfma_f32_16x16x32_bf16 v[112:115], v[136:139], v[194:197], v[112:115]
	v_mfma_f32_16x16x32_bf16 v[96:99], v[128:131], v[202:205], v[96:99]
	v_mfma_f32_16x16x32_bf16 v[88:91], v[136:139], v[202:205], v[88:91]
	v_mfma_f32_16x16x32_bf16 v[80:83], v[128:131], v[210:213], v[80:83]
	v_mfma_f32_16x16x32_bf16 v[72:75], v[136:139], v[210:213], v[72:75]
	v_mfma_f32_16x16x32_bf16 v[124:127], v[132:135], v[190:193], v[124:127]
	v_mfma_f32_16x16x32_bf16 v[120:123], v[140:143], v[190:193], v[120:123]
	v_mfma_f32_16x16x32_bf16 v[116:119], v[132:135], v[198:201], v[116:119]
	v_mfma_f32_16x16x32_bf16 v[112:115], v[140:143], v[198:201], v[112:115]
	v_mfma_f32_16x16x32_bf16 v[96:99], v[132:135], v[206:209], v[96:99]
	v_mfma_f32_16x16x32_bf16 v[88:91], v[140:143], v[206:209], v[88:91]
	v_mfma_f32_16x16x32_bf16 v[80:83], v[132:135], v[214:217], v[80:83]
	v_mfma_f32_16x16x32_bf16 v[72:75], v[140:143], v[214:217], v[72:75]
	v_mfma_f32_16x16x32_bf16 v[108:111], v[162:165], v[186:189], v[108:111]
	v_mfma_f32_16x16x32_bf16 v[104:107], v[178:181], v[186:189], v[104:107]
	ds_read_b128 v[186:189], v173 offset:16384
	v_mfma_f32_16x16x32_bf16 v[100:103], v[162:165], v[194:197], v[100:103]
	v_mfma_f32_16x16x32_bf16 v[92:95], v[178:181], v[194:197], v[92:95]
	ds_read_b128 v[194:197], v173 offset:18432
	v_mfma_f32_16x16x32_bf16 v[84:87], v[162:165], v[202:205], v[84:87]
	v_mfma_f32_16x16x32_bf16 v[76:79], v[178:181], v[202:205], v[76:79]
	ds_read_b128 v[202:205], v173 offset:20480
	v_mfma_f32_16x16x32_bf16 v[68:71], v[162:165], v[210:213], v[68:71]
	v_mfma_f32_16x16x32_bf16 v[64:67], v[178:181], v[210:213], v[64:67]
	ds_read_b128 v[210:213], v173 offset:22528
	v_mfma_f32_16x16x32_bf16 v[108:111], v[174:177], v[190:193], v[108:111]
	v_mfma_f32_16x16x32_bf16 v[104:107], v[182:185], v[190:193], v[104:107]
	ds_read_b128 v[190:193], v173 offset:17408
	v_mfma_f32_16x16x32_bf16 v[100:103], v[174:177], v[198:201], v[100:103]
	v_mfma_f32_16x16x32_bf16 v[92:95], v[182:185], v[198:201], v[92:95]
	ds_read_b128 v[198:201], v173 offset:19456
	v_mfma_f32_16x16x32_bf16 v[84:87], v[174:177], v[206:209], v[84:87]
	v_mfma_f32_16x16x32_bf16 v[76:79], v[182:185], v[206:209], v[76:79]
	ds_read_b128 v[206:209], v173 offset:21504
	v_mfma_f32_16x16x32_bf16 v[68:71], v[174:177], v[214:217], v[68:71]
	v_mfma_f32_16x16x32_bf16 v[64:67], v[182:185], v[214:217], v[64:67]
	ds_read_b128 v[214:217], v173 offset:23552
	s_barrier
	s_add_i32 s53, s43, s34
	v_lshl_add_u64 v[166:167], s[24:25], 0, v[146:147]
	s_mov_b32 m0, s53
	global_load_lds_dwordx4 v[166:167], off
	s_add_i32 m0, s53, 0x2000
	s_add_u32 s54, s24, 0xb0000
	v_lshl_add_u64 v[218:219], s[24:25], 0, v[150:151]
	s_addc_u32 s55, s25, 0
	s_add_i32 s53, s44, s34
	global_load_lds_dwordx4 v[218:219], off
	v_lshl_add_u64 v[220:221], s[54:55], 0, v[146:147]
	s_mov_b32 m0, s53
	v_lshl_add_u64 v[222:223], s[28:29], 0, v[148:149]
	global_load_lds_dwordx4 v[220:221], off
	v_lshl_add_u64 v[220:221], s[54:55], 0, v[150:151]
	s_add_i32 m0, s53, 0x2000
	s_nop 0
	global_load_lds_dwordx4 v[220:221], off
	v_lshl_add_u64 v[220:221], s[28:29], 0, v[144:145]
	s_mov_b32 m0, s35
	s_nop 0
	global_load_lds_dwordx4 v[220:221], off
	s_mov_b32 m0, s36
	s_nop 0
	global_load_lds_dwordx4 v[222:223], off
	s_waitcnt vmcnt(8)
	s_waitcnt lgkmcnt(0)
	s_barrier
; #define PG8_STAGE(bufoff, gbase, voff) do { _Pragma("unroll") for (int _i = 0; _i < 2; ++_i) \
;         __builtin_amdgcn_global_load_lds((const unsigned*)((const char*)(gbase) + (voff)[_i]), (PG8_LAS unsigned*)(lds + (bufoff) + ldsw + _i * 8192), 16, 0, 0); } while (0)
; #define PG8_LDA(dst, b, h) do { _Pragma("unroll") for (int m = 0; m < 4; ++m) _Pragma("unroll") for (int k = 0; k < 2; ++k) dst[m][k] = *(const PG8_LAS bf16x8*)(lds + PG8_SA(b, h) + aoff + m * 2048 + k * 1024); } while (0)
; #define PG8_LDB(dst, b, h) do { _Pragma("unroll") for (int n = 0; n < 2; ++n) _Pragma("unroll") for (int k = 0; k < 2; ++k) dst[n][k] = *(const PG8_LAS bf16x8*)(lds + PG8_SB(b, h) + boff + n * 2048 + k * 1024); } while (0)
; #define PG8_MMA(ai, bj, At, Bt) do { __builtin_amdgcn_s_setprio(1); _Pragma("unroll") for (int m = 0; m < 4; ++m) _Pragma("unroll") for (int n = 0; n < 2; ++n) _Pragma("unroll") for (int k = 0; k < 2; ++k) \
;         acc[ai][bj][m][n] = __builtin_amdgcn_mfma_f32_16x16x32_bf16(Bt[n][k], At[m][k], acc[ai][bj][m][n], 0, 0, 0); __builtin_amdgcn_s_setprio(0); } while (0)
; #define PG8_WAIT_V(n) asm volatile("s_waitcnt vmcnt(" #n ")" ::: "memory")
; #define PG8_WAIT_L(n) asm volatile("s_waitcnt lgkmcnt(" #n ")" ::: "memory")
; #define PG8_BAR __builtin_amdgcn_s_barrier()
; #define PG8_SCHED __builtin_amdgcn_sched_barrier(0)
; template <class Epi, class Sched, bool ALIGN_EPI = false, bool SP2 = false>
; __device__ __forceinline__ void gemm_phase(PG8_LAS unsigned char* lds, const Gemm g, const Sched& S, const Epi& E) {
;     ...
;             PG8_WAIT_V(8); PG8_WAIT_L(0); PG8_BAR; PG8_MMA(1, 0, At, B0); PG8_MMA(1, 1, At, B1); PG8_BAR; PG8_SCHED;
;             PG8_LDB(B0, 1, 0); PG8_LDB(B1, 1, 1); PG8_SCHED; PG8_LDA(At, 1, 0); PG8_STAGE(PG8_SA(0, 1), a2 + hstep, voffA);
;             PG8_WAIT_V(8); PG8_WAIT_L(0); PG8_BAR; PG8_MMA(0, 0, At, B0); PG8_MMA(0, 1, At, B1); PG8_BAR; PG8_SCHED;
;             PG8_LDA(At, 1, 1); PG8_STAGE(PG8_SB(1, 0), b3, voffB); PG8_STAGE(PG8_SB(1, 1), b3 + hstep, voffB); PG8_STAGE(PG8_SA(1, 0), a3, voffA);
	s_waitcnt lgkmcnt(0)
	v_mfma_f32_16x16x32_bf16 v[60:63], v[128:131], v[186:189], v[60:63]
	v_mfma_f32_16x16x32_bf16 v[56:59], v[136:139], v[186:189], v[56:59]
	v_mfma_f32_16x16x32_bf16 v[48:51], v[128:131], v[194:197], v[48:51]
	v_mfma_f32_16x16x32_bf16 v[40:43], v[136:139], v[194:197], v[40:43]
	v_mfma_f32_16x16x32_bf16 v[32:35], v[128:131], v[202:205], v[32:35]
	v_mfma_f32_16x16x32_bf16 v[24:27], v[136:139], v[202:205], v[24:27]
	v_mfma_f32_16x16x32_bf16 v[16:19], v[128:131], v[210:213], v[16:19]
	v_mfma_f32_16x16x32_bf16 v[8:11], v[136:139], v[210:213], v[8:11]
	v_mfma_f32_16x16x32_bf16 v[60:63], v[132:135], v[190:193], v[60:63]
	v_mfma_f32_16x16x32_bf16 v[56:59], v[140:143], v[190:193], v[56:59]
	v_mfma_f32_16x16x32_bf16 v[48:51], v[132:135], v[198:201], v[48:51]
	v_mfma_f32_16x16x32_bf16 v[40:43], v[140:143], v[198:201], v[40:43]
	v_mfma_f32_16x16x32_bf16 v[32:35], v[132:135], v[206:209], v[32:35]
	v_mfma_f32_16x16x32_bf16 v[24:27], v[140:143], v[206:209], v[24:27]
	v_mfma_f32_16x16x32_bf16 v[16:19], v[132:135], v[214:217], v[16:19]
	v_mfma_f32_16x16x32_bf16 v[8:11], v[140:143], v[214:217], v[8:11]
	v_mfma_f32_16x16x32_bf16 v[52:55], v[162:165], v[186:189], v[52:55]
	v_mfma_f32_16x16x32_bf16 v[44:47], v[178:181], v[186:189], v[44:47]
	v_mfma_f32_16x16x32_bf16 v[36:39], v[162:165], v[194:197], v[36:39]
	v_mfma_f32_16x16x32_bf16 v[28:31], v[178:181], v[194:197], v[28:31]
	v_mfma_f32_16x16x32_bf16 v[20:23], v[162:165], v[202:205], v[20:23]
	v_mfma_f32_16x16x32_bf16 v[12:15], v[178:181], v[202:205], v[12:15]
	v_mfma_f32_16x16x32_bf16 v[4:7], v[162:165], v[210:213], v[4:7]
	v_mfma_f32_16x16x32_bf16 v[0:3], v[178:181], v[210:213], v[0:3]
	v_mfma_f32_16x16x32_bf16 v[52:55], v[174:177], v[190:193], v[52:55]
	v_mfma_f32_16x16x32_bf16 v[44:47], v[182:185], v[190:193], v[44:47]
	v_mfma_f32_16x16x32_bf16 v[36:39], v[174:177], v[198:201], v[36:39]
	v_mfma_f32_16x16x32_bf16 v[28:31], v[182:185], v[198:201], v[28:31]
	v_mfma_f32_16x16x32_bf16 v[20:23], v[174:177], v[206:209], v[20:23]
	v_mfma_f32_16x16x32_bf16 v[12:15], v[182:185], v[206:209], v[12:15]
	v_mfma_f32_16x16x32_bf16 v[4:7], v[174:177], v[214:217], v[4:7]
	v_mfma_f32_16x16x32_bf16 v[0:3], v[182:185], v[214:217], v[0:3]
	s_barrier
	s_add_i32 s53, 0, 0x18000
	s_add_i32 s54, 0, 0x1c000
	v_add_u32_e32 v140, s53, v168
	v_add_u32_e32 v152, s54, v168
	ds_read_b128 v[128:131], v140
	ds_read_b128 v[132:135], v140 offset:1024
	ds_read_b128 v[136:139], v140 offset:2048
	ds_read_b128 v[140:143], v140 offset:3072
	ds_read_b128 v[162:165], v152
	ds_read_b128 v[174:177], v152 offset:1024
	ds_read_b128 v[178:181], v152 offset:2048
	ds_read_b128 v[182:185], v152 offset:3072
	s_add_u32 s28, s28, 0xb0000
	s_addc_u32 s29, s29, 0
	s_mov_b32 m0, s37
	v_lshl_add_u64 v[224:225], s[28:29], 0, v[144:145]
	ds_read_b128 v[186:189], v173 offset:32768
	ds_read_b128 v[190:193], v173 offset:33792
	ds_read_b128 v[194:197], v173 offset:34816
	ds_read_b128 v[198:201], v173 offset:35840
	ds_read_b128 v[202:205], v173 offset:36864
	ds_read_b128 v[206:209], v173 offset:37888
	ds_read_b128 v[210:213], v173 offset:38912
	ds_read_b128 v[214:217], v173 offset:39936
	global_load_lds_dwordx4 v[224:225], off
	v_lshl_add_u64 v[224:225], s[28:29], 0, v[148:149]
	s_mov_b32 m0, s38
	s_nop 0
	global_load_lds_dwordx4 v[224:225], off
	s_waitcnt vmcnt(8)
	s_waitcnt lgkmcnt(0)
	s_barrier
	s_waitcnt lgkmcnt(0)
	v_mfma_f32_16x16x32_bf16 v[124:127], v[128:131], v[186:189], v[124:127]
	v_mfma_f32_16x16x32_bf16 v[120:123], v[136:139], v[186:189], v[120:123]
	v_mfma_f32_16x16x32_bf16 v[116:119], v[128:131], v[194:197], v[116:119]
	v_mfma_f32_16x16x32_bf16 v[112:115], v[136:139], v[194:197], v[112:115]
	v_mfma_f32_16x16x32_bf16 v[96:99], v[128:131], v[202:205], v[96:99]
	v_mfma_f32_16x16x32_bf16 v[88:91], v[136:139], v[202:205], v[88:91]
	v_mfma_f32_16x16x32_bf16 v[80:83], v[128:131], v[210:213], v[80:83]
	v_mfma_f32_16x16x32_bf16 v[72:75], v[136:139], v[210:213], v[72:75]
	v_mfma_f32_16x16x32_bf16 v[124:127], v[132:135], v[190:193], v[124:127]
	v_mfma_f32_16x16x32_bf16 v[120:123], v[140:143], v[190:193], v[120:123]
	v_mfma_f32_16x16x32_bf16 v[116:119], v[132:135], v[198:201], v[116:119]
	v_mfma_f32_16x16x32_bf16 v[112:115], v[140:143], v[198:201], v[112:115]
	v_mfma_f32_16x16x32_bf16 v[96:99], v[132:135], v[206:209], v[96:99]
	v_mfma_f32_16x16x32_bf16 v[88:91], v[140:143], v[206:209], v[88:91]
	v_mfma_f32_16x16x32_bf16 v[80:83], v[132:135], v[214:217], v[80:83]
	v_mfma_f32_16x16x32_bf16 v[72:75], v[140:143], v[214:217], v[72:75]
	v_mfma_f32_16x16x32_bf16 v[108:111], v[162:165], v[186:189], v[108:111]
	v_mfma_f32_16x16x32_bf16 v[104:107], v[178:181], v[186:189], v[104:107]
	ds_read_b128 v[186:189], v173 offset:49152
	v_mfma_f32_16x16x32_bf16 v[100:103], v[162:165], v[194:197], v[100:103]
	v_mfma_f32_16x16x32_bf16 v[92:95], v[178:181], v[194:197], v[92:95]
	ds_read_b128 v[194:197], v173 offset:51200
	v_mfma_f32_16x16x32_bf16 v[84:87], v[162:165], v[202:205], v[84:87]
	v_mfma_f32_16x16x32_bf16 v[76:79], v[178:181], v[202:205], v[76:79]
	ds_read_b128 v[202:205], v173 offset:53248
	v_mfma_f32_16x16x32_bf16 v[68:71], v[162:165], v[210:213], v[68:71]
	v_mfma_f32_16x16x32_bf16 v[64:67], v[178:181], v[210:213], v[64:67]
	ds_read_b128 v[210:213], v173 offset:55296
	v_mfma_f32_16x16x32_bf16 v[108:111], v[174:177], v[190:193], v[108:111]
	v_mfma_f32_16x16x32_bf16 v[104:107], v[182:185], v[190:193], v[104:107]
	ds_read_b128 v[190:193], v173 offset:50176
	v_mfma_f32_16x16x32_bf16 v[100:103], v[174:177], v[198:201], v[100:103]
	v_mfma_f32_16x16x32_bf16 v[92:95], v[182:185], v[198:201], v[92:95]
	ds_read_b128 v[198:201], v173 offset:52224
	v_mfma_f32_16x16x32_bf16 v[84:87], v[174:177], v[206:209], v[84:87]
	v_mfma_f32_16x16x32_bf16 v[76:79], v[182:185], v[206:209], v[76:79]
	ds_read_b128 v[206:209], v173 offset:54272
	v_mfma_f32_16x16x32_bf16 v[68:71], v[174:177], v[214:217], v[68:71]
	v_mfma_f32_16x16x32_bf16 v[64:67], v[182:185], v[214:217], v[64:67]
	ds_read_b128 v[214:217], v173 offset:56320
	s_barrier
; #define PG8_STAGE(bufoff, gbase, voff) do { _Pragma("unroll") for (int _i = 0; _i < 2; ++_i) \
;         __builtin_amdgcn_global_load_lds((const unsigned*)((const char*)(gbase) + (voff)[_i]), (PG8_LAS unsigned*)(lds + (bufoff) + ldsw + _i * 8192), 16, 0, 0); } while (0)
; #define PG8_LDA(dst, b, h) do { _Pragma("unroll") for (int m = 0; m < 4; ++m) _Pragma("unroll") for (int k = 0; k < 2; ++k) dst[m][k] = *(const PG8_LAS bf16x8*)(lds + PG8_SA(b, h) + aoff + m * 2048 + k * 1024); } while (0)
; #define PG8_MMA(ai, bj, At, Bt) do { __builtin_amdgcn_s_setprio(1); _Pragma("unroll") for (int m = 0; m < 4; ++m) _Pragma("unroll") for (int n = 0; n < 2; ++n) _Pragma("unroll") for (int k = 0; k < 2; ++k) \
;         acc[ai][bj][m][n] = __builtin_amdgcn_mfma_f32_16x16x32_bf16(Bt[n][k], At[m][k], acc[ai][bj][m][n], 0, 0, 0); __builtin_amdgcn_s_setprio(0); } while (0)
; #define PG8_WAIT_V(n) asm volatile("s_waitcnt vmcnt(" #n ")" ::: "memory")
; #define PG8_WAIT_L(n) asm volatile("s_waitcnt lgkmcnt(" #n ")" ::: "memory")
; #define PG8_BAR __builtin_amdgcn_s_barrier()
; #define PG8_SCHED __builtin_amdgcn_sched_barrier(0)
; template <class Epi, class Sched, bool ALIGN_EPI = false, bool SP2 = false>
; __device__ __forceinline__ void gemm_phase(PG8_LAS unsigned char* lds, const Gemm g, const Sched& S, const Epi& E) {
;     ...
;             PG8_LDA(At, 1, 1); PG8_STAGE(PG8_SB(1, 0), b3, voffB); PG8_STAGE(PG8_SB(1, 1), b3 + hstep, voffB); PG8_STAGE(PG8_SA(1, 0), a3, voffA);
;             PG8_WAIT_V(8); PG8_WAIT_L(0); PG8_BAR; PG8_MMA(1, 0, At, B0); PG8_MMA(1, 1, At, B1); PG8_BAR; PG8_SCHED;
	s_add_i32 s28, s53, s34
	v_lshl_add_u64 v[166:167], v[166:167], 0, s[14:15]
	s_mov_b32 m0, s28
	global_load_lds_dwordx4 v[166:167], off
	s_add_i32 m0, s28, 0x2000
	s_add_u32 s24, s24, 0xb0080
	v_lshl_add_u64 v[166:167], v[218:219], 0, s[14:15]
	s_addc_u32 s25, s25, 0
	s_add_i32 s28, s54, s34
	global_load_lds_dwordx4 v[166:167], off
	v_lshl_add_u64 v[166:167], s[24:25], 0, v[146:147]
	s_mov_b32 m0, s28
	s_nop 0
	global_load_lds_dwordx4 v[166:167], off
	v_lshl_add_u64 v[166:167], s[24:25], 0, v[150:151]
	s_add_i32 m0, s28, 0x2000
	s_nop 0
	global_load_lds_dwordx4 v[166:167], off
	v_lshl_add_u64 v[166:167], v[220:221], 0, s[14:15]
	s_mov_b32 m0, s40
	s_nop 0
	global_load_lds_dwordx4 v[166:167], off
	v_lshl_add_u64 v[166:167], v[222:223], 0, s[14:15]
	s_mov_b32 m0, s41
	s_nop 0
	global_load_lds_dwordx4 v[166:167], off
	s_waitcnt vmcnt(8)
	s_waitcnt lgkmcnt(0)
	s_barrier
	s_waitcnt lgkmcnt(0)
	v_mfma_f32_16x16x32_bf16 v[60:63], v[128:131], v[186:189], v[60:63]
	v_mfma_f32_16x16x32_bf16 v[56:59], v[136:139], v[186:189], v[56:59]
	v_mfma_f32_16x16x32_bf16 v[48:51], v[128:131], v[194:197], v[48:51]
	v_mfma_f32_16x16x32_bf16 v[40:43], v[136:139], v[194:197], v[40:43]
	v_mfma_f32_16x16x32_bf16 v[32:35], v[128:131], v[202:205], v[32:35]
	v_mfma_f32_16x16x32_bf16 v[24:27], v[136:139], v[202:205], v[24:27]
	v_mfma_f32_16x16x32_bf16 v[16:19], v[128:131], v[210:213], v[16:19]
	v_mfma_f32_16x16x32_bf16 v[8:11], v[136:139], v[210:213], v[8:11]
	v_mfma_f32_16x16x32_bf16 v[60:63], v[132:135], v[190:193], v[60:63]
	v_mfma_f32_16x16x32_bf16 v[56:59], v[140:143], v[190:193], v[56:59]
	v_mfma_f32_16x16x32_bf16 v[48:51], v[132:135], v[198:201], v[48:51]
	v_mfma_f32_16x16x32_bf16 v[40:43], v[140:143], v[198:201], v[40:43]
	v_mfma_f32_16x16x32_bf16 v[32:35], v[132:135], v[206:209], v[32:35]
	v_mfma_f32_16x16x32_bf16 v[24:27], v[140:143], v[206:209], v[24:27]
	v_mfma_f32_16x16x32_bf16 v[16:19], v[132:135], v[214:217], v[16:19]
	v_mfma_f32_16x16x32_bf16 v[8:11], v[140:143], v[214:217], v[8:11]
	v_mfma_f32_16x16x32_bf16 v[52:55], v[162:165], v[186:189], v[52:55]
	v_mfma_f32_16x16x32_bf16 v[44:47], v[178:181], v[186:189], v[44:47]
	v_mfma_f32_16x16x32_bf16 v[36:39], v[162:165], v[194:197], v[36:39]
	v_mfma_f32_16x16x32_bf16 v[28:31], v[178:181], v[194:197], v[28:31]
	v_mfma_f32_16x16x32_bf16 v[20:23], v[162:165], v[202:205], v[20:23]
	v_mfma_f32_16x16x32_bf16 v[12:15], v[178:181], v[202:205], v[12:15]
	v_mfma_f32_16x16x32_bf16 v[4:7], v[162:165], v[210:213], v[4:7]
	v_mfma_f32_16x16x32_bf16 v[0:3], v[178:181], v[210:213], v[0:3]
	v_mfma_f32_16x16x32_bf16 v[52:55], v[174:177], v[190:193], v[52:55]
	v_mfma_f32_16x16x32_bf16 v[44:47], v[182:185], v[190:193], v[44:47]
	v_mfma_f32_16x16x32_bf16 v[36:39], v[174:177], v[198:201], v[36:39]
	v_mfma_f32_16x16x32_bf16 v[28:31], v[182:185], v[198:201], v[28:31]
	v_mfma_f32_16x16x32_bf16 v[20:23], v[174:177], v[206:209], v[20:23]
	v_mfma_f32_16x16x32_bf16 v[12:15], v[182:185], v[206:209], v[12:15]
	v_mfma_f32_16x16x32_bf16 v[4:7], v[174:177], v[214:217], v[4:7]
	v_mfma_f32_16x16x32_bf16 v[0:3], v[182:185], v[214:217], v[0:3]
	s_barrier
	s_add_i32 s52, s52, 2
	s_add_u32 s22, s22, 0x100
	s_addc_u32 s23, s23, 0
	s_add_u32 s50, s50, 0x100
	s_addc_u32 s51, s51, 0
	s_cmp_gt_u32 s52, 41
	s_cbranch_scc0 .LBB0_674
	s_setprio 0
	s_and_b64 vcc, exec, s[16:17]
	s_cbranch_vccz .LBB0_677
	s_barrier
